# M_MIX non-rotary epilogue re-generated: straight-line path per column kind (silu/plain/sigmoid)
# speedup vs baseline: 1.0175x; 1.0076x over previous
; __device__ __forceinline__ float sigm_f(float v) { return __builtin_amdgcn_rcpf(1.0f + __builtin_amdgcn_exp2f(-1.44269504f * v)); }
; __device__ __forceinline__ float silu_f(float v) { return v * sigm_f(v); }
;     __device__ __forceinline__ void operator()(const f32x4 (&acc)[2][2][4][2], const Unit& u, int wr, int wc, int fr, int fq) const {
;     ...
; #pragma unroll
;                 for (int ai = 0; ai < 2; ++ai)
; #pragma unroll
;                     for (int m = 0; m < 4; ++m) { const int row = row0 + ai * HALF + m * 16; const float rsv = __builtin_amdgcn_rsqf(rs[row] * (1.0f / 1024.0f) + 1e-6f);
;                         bf16_t* rowp = O + (size_t)row * ldc + u.pn * BM + cw;
; #pragma unroll
;                         for (int bj = 0; bj < 2; ++bj) { f32x4 v0 = acc[ai][bj][m][0] * rsv, v1 = acc[ai][bj][m][1] * rsv;
;                             if (sub == 1) {
; #pragma unroll
;                                 for (int e = 0; e < 4; ++e) { v0[e] = silu_f(v0[e]); v1[e] = silu_f(v1[e]); } }
;                             else if (sub == 3) {
; #pragma unroll
;                                 for (int e = 0; e < 4; ++e) { v0[e] = sigm_f(v0[e]); v1[e] = sigm_f(v1[e]); } }
;                             store8(rowp + bj * HALF, v0, v1); } }
.LBB0_486:
	s_andn2_b64 vcc, exec, s[6:7]
	s_cbranch_vccnz .LBB0_587
	v_ashrrev_i32_e32 v165, 31, v164
	v_lshl_add_u64 v[128:129], v[164:165], 2, s[26:27]
	global_load_dword v130, v[128:129], off
	global_load_dword v247, v[128:129], off offset:64
	global_load_dword v248, v[128:129], off offset:128
	global_load_dword v249, v[128:129], off offset:192
	global_load_dword v250, v[128:129], off offset:512
	global_load_dword v252, v[128:129], off offset:576
	global_load_dword v253, v[128:129], off offset:640
	global_load_dword v255, v[128:129], off offset:704
	s_lshl_b32 s62, s40, 8
	s_cmp_lt_i32 s40, 4
	s_mov_b64 s[6:7], -1
	s_waitcnt vmcnt(0) lgkmcnt(0)
	v_fmamk_f32 v130, v130, 0x3a800000, v237
	v_rsq_f32_e32 v130, v130
	s_cbranch_scc1 .LBB0_585
	s_cmp_lt_u32 s40, 12
	s_cselect_b32 s6, 2, 3
	s_cmp_gt_u32 s40, 7
	s_cselect_b32 s38, s6, 1
	v_mov_b32_e32 v188, 1.0
	v_mov_b32_e32 v189, 1.0
	s_cmp_eq_u32 s38, 2
	s_cbranch_scc1 .Lmix_plain
	s_cmp_eq_u32 s38, 1
	s_cbranch_scc1 .Lmix_silu
	v_mov_b32_e32 v182, v130
	v_mad_i64_i32 v[172:173], s[98:99], s82, v164, 0
	v_lshl_add_u64 v[172:173], v[172:173], 1, s[84:85]
	v_lshl_add_u64 v[172:173], s[62:63], 1, v[172:173]
	v_lshl_add_u64 v[172:173], v[148:149], 1, v[172:173]
	v_mul_f32_e32 v184, 0xbfb8aa3b, v182
	v_pk_mul_f32 v[190:191], v[124:125], v[184:185] op_sel_hi:[1,0]
	v_pk_mul_f32 v[192:193], v[126:127], v[184:185] op_sel_hi:[1,0]
	v_pk_mul_f32 v[194:195], v[120:121], v[184:185] op_sel_hi:[1,0]
	v_pk_mul_f32 v[196:197], v[122:123], v[184:185] op_sel_hi:[1,0]
	v_exp_f32_e32 v190, v190
	v_exp_f32_e32 v191, v191
	v_exp_f32_e32 v192, v192
	v_exp_f32_e32 v193, v193
	v_exp_f32_e32 v194, v194
	v_exp_f32_e32 v195, v195
	v_exp_f32_e32 v196, v196
	v_exp_f32_e32 v197, v197
	s_nop 0
	v_pk_add_f32 v[190:191], v[190:191], v[188:189]
	v_pk_add_f32 v[192:193], v[192:193], v[188:189]
	v_pk_add_f32 v[194:195], v[194:195], v[188:189]
	v_pk_add_f32 v[196:197], v[196:197], v[188:189]
	v_rcp_f32_e32 v190, v190
	v_rcp_f32_e32 v191, v191
	v_rcp_f32_e32 v192, v192
	v_rcp_f32_e32 v193, v193
	v_rcp_f32_e32 v194, v194
	v_rcp_f32_e32 v195, v195
	v_rcp_f32_e32 v196, v196
	v_rcp_f32_e32 v197, v197
	s_nop 0
	v_cvt_pk_bf16_f32 v134, v190, v191
	v_cvt_pk_bf16_f32 v135, v192, v193
	v_cvt_pk_bf16_f32 v136, v194, v195
	v_cvt_pk_bf16_f32 v137, v196, v197
	flat_store_dwordx4 v[172:173], v[134:137]
	v_pk_mul_f32 v[190:191], v[108:109], v[184:185] op_sel_hi:[1,0]
	v_pk_mul_f32 v[192:193], v[110:111], v[184:185] op_sel_hi:[1,0]
	v_pk_mul_f32 v[194:195], v[104:105], v[184:185] op_sel_hi:[1,0]
	v_pk_mul_f32 v[196:197], v[106:107], v[184:185] op_sel_hi:[1,0]
	v_exp_f32_e32 v190, v190
	v_exp_f32_e32 v191, v191
	v_exp_f32_e32 v192, v192
	v_exp_f32_e32 v193, v193
	v_exp_f32_e32 v194, v194
	v_exp_f32_e32 v195, v195
	v_exp_f32_e32 v196, v196
	v_exp_f32_e32 v197, v197
	s_nop 0
	v_pk_add_f32 v[190:191], v[190:191], v[188:189]
	v_pk_add_f32 v[192:193], v[192:193], v[188:189]
	v_pk_add_f32 v[194:195], v[194:195], v[188:189]
	v_pk_add_f32 v[196:197], v[196:197], v[188:189]
	v_rcp_f32_e32 v190, v190
	v_rcp_f32_e32 v191, v191
	v_rcp_f32_e32 v192, v192
	v_rcp_f32_e32 v193, v193
	v_rcp_f32_e32 v194, v194
	v_rcp_f32_e32 v195, v195
	v_rcp_f32_e32 v196, v196
	v_rcp_f32_e32 v197, v197
	s_nop 0
	v_cvt_pk_bf16_f32 v212, v190, v191
	v_cvt_pk_bf16_f32 v213, v192, v193
	v_cvt_pk_bf16_f32 v214, v194, v195
	v_cvt_pk_bf16_f32 v215, v196, v197
	flat_store_dwordx4 v[172:173], v[212:215] offset:256
	v_fmamk_f32 v206, v247, 0x3a800000, v237
	v_rsq_f32_e32 v182, v206
	v_add_u32_e32 v207, 0x10, v164
	v_mad_i64_i32 v[172:173], s[98:99], s82, v207, 0
	v_lshl_add_u64 v[172:173], v[172:173], 1, s[84:85]
	v_lshl_add_u64 v[172:173], s[62:63], 1, v[172:173]
	v_lshl_add_u64 v[172:173], v[148:149], 1, v[172:173]
	v_mul_f32_e32 v184, 0xbfb8aa3b, v182
	v_pk_mul_f32 v[190:191], v[116:117], v[184:185] op_sel_hi:[1,0]
	v_pk_mul_f32 v[192:193], v[118:119], v[184:185] op_sel_hi:[1,0]
	v_pk_mul_f32 v[194:195], v[112:113], v[184:185] op_sel_hi:[1,0]
	v_pk_mul_f32 v[196:197], v[114:115], v[184:185] op_sel_hi:[1,0]
	v_exp_f32_e32 v190, v190
	v_exp_f32_e32 v191, v191
	v_exp_f32_e32 v192, v192
	v_exp_f32_e32 v193, v193
	v_exp_f32_e32 v194, v194
	v_exp_f32_e32 v195, v195
	v_exp_f32_e32 v196, v196
	v_exp_f32_e32 v197, v197
	s_nop 0
	v_pk_add_f32 v[190:191], v[190:191], v[188:189]
	v_pk_add_f32 v[192:193], v[192:193], v[188:189]
	v_pk_add_f32 v[194:195], v[194:195], v[188:189]
	v_pk_add_f32 v[196:197], v[196:197], v[188:189]
	v_rcp_f32_e32 v190, v190
	v_rcp_f32_e32 v191, v191
	v_rcp_f32_e32 v192, v192
	v_rcp_f32_e32 v193, v193
	v_rcp_f32_e32 v194, v194
	v_rcp_f32_e32 v195, v195
	v_rcp_f32_e32 v196, v196
	v_rcp_f32_e32 v197, v197
	s_nop 0
	v_cvt_pk_bf16_f32 v134, v190, v191
	v_cvt_pk_bf16_f32 v135, v192, v193
	v_cvt_pk_bf16_f32 v136, v194, v195
	v_cvt_pk_bf16_f32 v137, v196, v197
	flat_store_dwordx4 v[172:173], v[134:137]
	v_pk_mul_f32 v[190:191], v[92:93], v[184:185] op_sel_hi:[1,0]
	v_pk_mul_f32 v[192:193], v[94:95], v[184:185] op_sel_hi:[1,0]
	v_pk_mul_f32 v[194:195], v[88:89], v[184:185] op_sel_hi:[1,0]
	v_pk_mul_f32 v[196:197], v[90:91], v[184:185] op_sel_hi:[1,0]
	v_exp_f32_e32 v190, v190
	v_exp_f32_e32 v191, v191
	v_exp_f32_e32 v192, v192
	v_exp_f32_e32 v193, v193
	v_exp_f32_e32 v194, v194
	v_exp_f32_e32 v195, v195
	v_exp_f32_e32 v196, v196
	v_exp_f32_e32 v197, v197
	s_nop 0
	v_pk_add_f32 v[190:191], v[190:191], v[188:189]
	v_pk_add_f32 v[192:193], v[192:193], v[188:189]
	v_pk_add_f32 v[194:195], v[194:195], v[188:189]
	v_pk_add_f32 v[196:197], v[196:197], v[188:189]
	v_rcp_f32_e32 v190, v190
	v_rcp_f32_e32 v191, v191
	v_rcp_f32_e32 v192, v192
	v_rcp_f32_e32 v193, v193
	v_rcp_f32_e32 v194, v194
; __device__ __forceinline__ float sigm_f(float v) { return __builtin_amdgcn_rcpf(1.0f + __builtin_amdgcn_exp2f(-1.44269504f * v)); }
; __device__ __forceinline__ float silu_f(float v) { return v * sigm_f(v); }
;     __device__ __forceinline__ void operator()(const f32x4 (&acc)[2][2][4][2], const Unit& u, int wr, int wc, int fr, int fq) const {
;     ...
; #pragma unroll
;                 for (int ai = 0; ai < 2; ++ai)
; #pragma unroll
;                     for (int m = 0; m < 4; ++m) { const int row = row0 + ai * HALF + m * 16; const float rsv = __builtin_amdgcn_rsqf(rs[row] * (1.0f / 1024.0f) + 1e-6f);
;                         bf16_t* rowp = O + (size_t)row * ldc + u.pn * BM + cw;
; #pragma unroll
;                         for (int bj = 0; bj < 2; ++bj) { f32x4 v0 = acc[ai][bj][m][0] * rsv, v1 = acc[ai][bj][m][1] * rsv;
;                             if (sub == 1) {
; #pragma unroll
;                                 for (int e = 0; e < 4; ++e) { v0[e] = silu_f(v0[e]); v1[e] = silu_f(v1[e]); } }
;                             else if (sub == 3) {
; #pragma unroll
;                                 for (int e = 0; e < 4; ++e) { v0[e] = sigm_f(v0[e]); v1[e] = sigm_f(v1[e]); } }
;                             store8(rowp + bj * HALF, v0, v1); } }
	v_rcp_f32_e32 v195, v195
	v_rcp_f32_e32 v196, v196
	v_rcp_f32_e32 v197, v197
	s_nop 0
	v_cvt_pk_bf16_f32 v212, v190, v191
	v_cvt_pk_bf16_f32 v213, v192, v193
	v_cvt_pk_bf16_f32 v214, v194, v195
	v_cvt_pk_bf16_f32 v215, v196, v197
	flat_store_dwordx4 v[172:173], v[212:215] offset:256
	v_fmamk_f32 v206, v248, 0x3a800000, v237
	v_rsq_f32_e32 v182, v206
	v_add_u32_e32 v207, 0x20, v164
	v_mad_i64_i32 v[172:173], s[98:99], s82, v207, 0
	v_lshl_add_u64 v[172:173], v[172:173], 1, s[84:85]
	v_lshl_add_u64 v[172:173], s[62:63], 1, v[172:173]
	v_lshl_add_u64 v[172:173], v[148:149], 1, v[172:173]
	v_mul_f32_e32 v184, 0xbfb8aa3b, v182
	v_pk_mul_f32 v[190:191], v[100:101], v[184:185] op_sel_hi:[1,0]
	v_pk_mul_f32 v[192:193], v[102:103], v[184:185] op_sel_hi:[1,0]
	v_pk_mul_f32 v[194:195], v[96:97], v[184:185] op_sel_hi:[1,0]
	v_pk_mul_f32 v[196:197], v[98:99], v[184:185] op_sel_hi:[1,0]
	v_exp_f32_e32 v190, v190
	v_exp_f32_e32 v191, v191
	v_exp_f32_e32 v192, v192
	v_exp_f32_e32 v193, v193
	v_exp_f32_e32 v194, v194
	v_exp_f32_e32 v195, v195
	v_exp_f32_e32 v196, v196
	v_exp_f32_e32 v197, v197
	s_nop 0
	v_pk_add_f32 v[190:191], v[190:191], v[188:189]
	v_pk_add_f32 v[192:193], v[192:193], v[188:189]
	v_pk_add_f32 v[194:195], v[194:195], v[188:189]
	v_pk_add_f32 v[196:197], v[196:197], v[188:189]
	v_rcp_f32_e32 v190, v190
	v_rcp_f32_e32 v191, v191
	v_rcp_f32_e32 v192, v192
	v_rcp_f32_e32 v193, v193
	v_rcp_f32_e32 v194, v194
	v_rcp_f32_e32 v195, v195
	v_rcp_f32_e32 v196, v196
	v_rcp_f32_e32 v197, v197
	s_nop 0
	v_cvt_pk_bf16_f32 v134, v190, v191
	v_cvt_pk_bf16_f32 v135, v192, v193
	v_cvt_pk_bf16_f32 v136, v194, v195
	v_cvt_pk_bf16_f32 v137, v196, v197
	flat_store_dwordx4 v[172:173], v[134:137]
	v_pk_mul_f32 v[190:191], v[76:77], v[184:185] op_sel_hi:[1,0]
	v_pk_mul_f32 v[192:193], v[78:79], v[184:185] op_sel_hi:[1,0]
	v_pk_mul_f32 v[194:195], v[72:73], v[184:185] op_sel_hi:[1,0]
	v_pk_mul_f32 v[196:197], v[74:75], v[184:185] op_sel_hi:[1,0]
	v_exp_f32_e32 v190, v190
	v_exp_f32_e32 v191, v191
	v_exp_f32_e32 v192, v192
	v_exp_f32_e32 v193, v193
	v_exp_f32_e32 v194, v194
	v_exp_f32_e32 v195, v195
	v_exp_f32_e32 v196, v196
	v_exp_f32_e32 v197, v197
	s_nop 0
	v_pk_add_f32 v[190:191], v[190:191], v[188:189]
	v_pk_add_f32 v[192:193], v[192:193], v[188:189]
	v_pk_add_f32 v[194:195], v[194:195], v[188:189]
	v_pk_add_f32 v[196:197], v[196:197], v[188:189]
	v_rcp_f32_e32 v190, v190
	v_rcp_f32_e32 v191, v191
	v_rcp_f32_e32 v192, v192
	v_rcp_f32_e32 v193, v193
	v_rcp_f32_e32 v194, v194
	v_rcp_f32_e32 v195, v195
	v_rcp_f32_e32 v196, v196
	v_rcp_f32_e32 v197, v197
	s_nop 0
	v_cvt_pk_bf16_f32 v212, v190, v191
	v_cvt_pk_bf16_f32 v213, v192, v193
	v_cvt_pk_bf16_f32 v214, v194, v195
	v_cvt_pk_bf16_f32 v215, v196, v197
	flat_store_dwordx4 v[172:173], v[212:215] offset:256
	v_fmamk_f32 v206, v249, 0x3a800000, v237
	v_rsq_f32_e32 v182, v206
	v_add_u32_e32 v207, 0x30, v164
	v_mad_i64_i32 v[172:173], s[98:99], s82, v207, 0
	v_lshl_add_u64 v[172:173], v[172:173], 1, s[84:85]
	v_lshl_add_u64 v[172:173], s[62:63], 1, v[172:173]
	v_lshl_add_u64 v[172:173], v[148:149], 1, v[172:173]
	v_mul_f32_e32 v184, 0xbfb8aa3b, v182
	v_pk_mul_f32 v[190:191], v[84:85], v[184:185] op_sel_hi:[1,0]
	v_pk_mul_f32 v[192:193], v[86:87], v[184:185] op_sel_hi:[1,0]
	v_pk_mul_f32 v[194:195], v[80:81], v[184:185] op_sel_hi:[1,0]
	v_pk_mul_f32 v[196:197], v[82:83], v[184:185] op_sel_hi:[1,0]
	v_exp_f32_e32 v190, v190
	v_exp_f32_e32 v191, v191
	v_exp_f32_e32 v192, v192
	v_exp_f32_e32 v193, v193
	v_exp_f32_e32 v194, v194
	v_exp_f32_e32 v195, v195
	v_exp_f32_e32 v196, v196
	v_exp_f32_e32 v197, v197
	s_nop 0
	v_pk_add_f32 v[190:191], v[190:191], v[188:189]
	v_pk_add_f32 v[192:193], v[192:193], v[188:189]
	v_pk_add_f32 v[194:195], v[194:195], v[188:189]
	v_pk_add_f32 v[196:197], v[196:197], v[188:189]
	v_rcp_f32_e32 v190, v190
	v_rcp_f32_e32 v191, v191
	v_rcp_f32_e32 v192, v192
	v_rcp_f32_e32 v193, v193
	v_rcp_f32_e32 v194, v194
	v_rcp_f32_e32 v195, v195
	v_rcp_f32_e32 v196, v196
	v_rcp_f32_e32 v197, v197
	s_nop 0
	v_cvt_pk_bf16_f32 v134, v190, v191
	v_cvt_pk_bf16_f32 v135, v192, v193
	v_cvt_pk_bf16_f32 v136, v194, v195
	v_cvt_pk_bf16_f32 v137, v196, v197
	flat_store_dwordx4 v[172:173], v[134:137]
	v_pk_mul_f32 v[190:191], v[68:69], v[184:185] op_sel_hi:[1,0]
	v_pk_mul_f32 v[192:193], v[70:71], v[184:185] op_sel_hi:[1,0]
	v_pk_mul_f32 v[194:195], v[64:65], v[184:185] op_sel_hi:[1,0]
	v_pk_mul_f32 v[196:197], v[66:67], v[184:185] op_sel_hi:[1,0]
	v_exp_f32_e32 v190, v190
	v_exp_f32_e32 v191, v191
	v_exp_f32_e32 v192, v192
	v_exp_f32_e32 v193, v193
	v_exp_f32_e32 v194, v194
	v_exp_f32_e32 v195, v195
	v_exp_f32_e32 v196, v196
	v_exp_f32_e32 v197, v197
	s_nop 0
	v_pk_add_f32 v[190:191], v[190:191], v[188:189]
	v_pk_add_f32 v[192:193], v[192:193], v[188:189]
	v_pk_add_f32 v[194:195], v[194:195], v[188:189]
	v_pk_add_f32 v[196:197], v[196:197], v[188:189]
	v_rcp_f32_e32 v190, v190
	v_rcp_f32_e32 v191, v191
	v_rcp_f32_e32 v192, v192
	v_rcp_f32_e32 v193, v193
	v_rcp_f32_e32 v194, v194
	v_rcp_f32_e32 v195, v195
	v_rcp_f32_e32 v196, v196
	v_rcp_f32_e32 v197, v197
	s_nop 0
	v_cvt_pk_bf16_f32 v212, v190, v191
	v_cvt_pk_bf16_f32 v213, v192, v193
	v_cvt_pk_bf16_f32 v214, v194, v195
	v_cvt_pk_bf16_f32 v215, v196, v197
	flat_store_dwordx4 v[172:173], v[212:215] offset:256
	v_fmamk_f32 v206, v250, 0x3a800000, v237
	v_rsq_f32_e32 v182, v206
	v_add_u32_e32 v207, 0x80, v164
	v_mad_i64_i32 v[172:173], s[98:99], s82, v207, 0
	v_lshl_add_u64 v[172:173], v[172:173], 1, s[84:85]
	v_lshl_add_u64 v[172:173], s[62:63], 1, v[172:173]
	v_lshl_add_u64 v[172:173], v[148:149], 1, v[172:173]
	v_mul_f32_e32 v184, 0xbfb8aa3b, v182
; __device__ __forceinline__ float sigm_f(float v) { return __builtin_amdgcn_rcpf(1.0f + __builtin_amdgcn_exp2f(-1.44269504f * v)); }
; __device__ __forceinline__ float silu_f(float v) { return v * sigm_f(v); }
;     __device__ __forceinline__ void operator()(const f32x4 (&acc)[2][2][4][2], const Unit& u, int wr, int wc, int fr, int fq) const {
;     ...
; #pragma unroll
;                 for (int ai = 0; ai < 2; ++ai)
; #pragma unroll
;                     for (int m = 0; m < 4; ++m) { const int row = row0 + ai * HALF + m * 16; const float rsv = __builtin_amdgcn_rsqf(rs[row] * (1.0f / 1024.0f) + 1e-6f);
;                         bf16_t* rowp = O + (size_t)row * ldc + u.pn * BM + cw;
; #pragma unroll
;                         for (int bj = 0; bj < 2; ++bj) { f32x4 v0 = acc[ai][bj][m][0] * rsv, v1 = acc[ai][bj][m][1] * rsv;
;                             if (sub == 1) {
; #pragma unroll
;                                 for (int e = 0; e < 4; ++e) { v0[e] = silu_f(v0[e]); v1[e] = silu_f(v1[e]); } }
;                             else if (sub == 3) {
; #pragma unroll
;                                 for (int e = 0; e < 4; ++e) { v0[e] = sigm_f(v0[e]); v1[e] = sigm_f(v1[e]); } }
;                             store8(rowp + bj * HALF, v0, v1); } }
	v_pk_mul_f32 v[190:191], v[60:61], v[184:185] op_sel_hi:[1,0]
	v_pk_mul_f32 v[192:193], v[62:63], v[184:185] op_sel_hi:[1,0]
	v_pk_mul_f32 v[194:195], v[56:57], v[184:185] op_sel_hi:[1,0]
	v_pk_mul_f32 v[196:197], v[58:59], v[184:185] op_sel_hi:[1,0]
	v_exp_f32_e32 v190, v190
	v_exp_f32_e32 v191, v191
	v_exp_f32_e32 v192, v192
	v_exp_f32_e32 v193, v193
	v_exp_f32_e32 v194, v194
	v_exp_f32_e32 v195, v195
	v_exp_f32_e32 v196, v196
	v_exp_f32_e32 v197, v197
	s_nop 0
	v_pk_add_f32 v[190:191], v[190:191], v[188:189]
	v_pk_add_f32 v[192:193], v[192:193], v[188:189]
	v_pk_add_f32 v[194:195], v[194:195], v[188:189]
	v_pk_add_f32 v[196:197], v[196:197], v[188:189]
	v_rcp_f32_e32 v190, v190
	v_rcp_f32_e32 v191, v191
	v_rcp_f32_e32 v192, v192
	v_rcp_f32_e32 v193, v193
	v_rcp_f32_e32 v194, v194
	v_rcp_f32_e32 v195, v195
	v_rcp_f32_e32 v196, v196
	v_rcp_f32_e32 v197, v197
	s_nop 0
	v_cvt_pk_bf16_f32 v134, v190, v191
	v_cvt_pk_bf16_f32 v135, v192, v193
	v_cvt_pk_bf16_f32 v136, v194, v195
	v_cvt_pk_bf16_f32 v137, v196, v197
	flat_store_dwordx4 v[172:173], v[134:137]
	v_pk_mul_f32 v[190:191], v[44:45], v[184:185] op_sel_hi:[1,0]
	v_pk_mul_f32 v[192:193], v[46:47], v[184:185] op_sel_hi:[1,0]
	v_pk_mul_f32 v[194:195], v[40:41], v[184:185] op_sel_hi:[1,0]
	v_pk_mul_f32 v[196:197], v[42:43], v[184:185] op_sel_hi:[1,0]
	v_exp_f32_e32 v190, v190
	v_exp_f32_e32 v191, v191
	v_exp_f32_e32 v192, v192
	v_exp_f32_e32 v193, v193
	v_exp_f32_e32 v194, v194
	v_exp_f32_e32 v195, v195
	v_exp_f32_e32 v196, v196
	v_exp_f32_e32 v197, v197
	s_nop 0
	v_pk_add_f32 v[190:191], v[190:191], v[188:189]
	v_pk_add_f32 v[192:193], v[192:193], v[188:189]
	v_pk_add_f32 v[194:195], v[194:195], v[188:189]
	v_pk_add_f32 v[196:197], v[196:197], v[188:189]
	v_rcp_f32_e32 v190, v190
	v_rcp_f32_e32 v191, v191
	v_rcp_f32_e32 v192, v192
	v_rcp_f32_e32 v193, v193
	v_rcp_f32_e32 v194, v194
	v_rcp_f32_e32 v195, v195
	v_rcp_f32_e32 v196, v196
	v_rcp_f32_e32 v197, v197
	s_nop 0
	v_cvt_pk_bf16_f32 v212, v190, v191
	v_cvt_pk_bf16_f32 v213, v192, v193
	v_cvt_pk_bf16_f32 v214, v194, v195
	v_cvt_pk_bf16_f32 v215, v196, v197
	flat_store_dwordx4 v[172:173], v[212:215] offset:256
	v_fmamk_f32 v206, v252, 0x3a800000, v237
	v_rsq_f32_e32 v182, v206
	v_add_u32_e32 v207, 0x90, v164
	v_mad_i64_i32 v[172:173], s[98:99], s82, v207, 0
	v_lshl_add_u64 v[172:173], v[172:173], 1, s[84:85]
	v_lshl_add_u64 v[172:173], s[62:63], 1, v[172:173]
	v_lshl_add_u64 v[172:173], v[148:149], 1, v[172:173]
	v_mul_f32_e32 v184, 0xbfb8aa3b, v182
	v_pk_mul_f32 v[190:191], v[52:53], v[184:185] op_sel_hi:[1,0]
	v_pk_mul_f32 v[192:193], v[54:55], v[184:185] op_sel_hi:[1,0]
	v_pk_mul_f32 v[194:195], v[48:49], v[184:185] op_sel_hi:[1,0]
	v_pk_mul_f32 v[196:197], v[50:51], v[184:185] op_sel_hi:[1,0]
	v_exp_f32_e32 v190, v190
	v_exp_f32_e32 v191, v191
	v_exp_f32_e32 v192, v192
	v_exp_f32_e32 v193, v193
	v_exp_f32_e32 v194, v194
	v_exp_f32_e32 v195, v195
	v_exp_f32_e32 v196, v196
	v_exp_f32_e32 v197, v197
	s_nop 0
	v_pk_add_f32 v[190:191], v[190:191], v[188:189]
	v_pk_add_f32 v[192:193], v[192:193], v[188:189]
	v_pk_add_f32 v[194:195], v[194:195], v[188:189]
	v_pk_add_f32 v[196:197], v[196:197], v[188:189]
	v_rcp_f32_e32 v190, v190
	v_rcp_f32_e32 v191, v191
	v_rcp_f32_e32 v192, v192
	v_rcp_f32_e32 v193, v193
	v_rcp_f32_e32 v194, v194
	v_rcp_f32_e32 v195, v195
	v_rcp_f32_e32 v196, v196
	v_rcp_f32_e32 v197, v197
	s_nop 0
	v_cvt_pk_bf16_f32 v134, v190, v191
	v_cvt_pk_bf16_f32 v135, v192, v193
	v_cvt_pk_bf16_f32 v136, v194, v195
	v_cvt_pk_bf16_f32 v137, v196, v197
	flat_store_dwordx4 v[172:173], v[134:137]
	v_pk_mul_f32 v[190:191], v[28:29], v[184:185] op_sel_hi:[1,0]
	v_pk_mul_f32 v[192:193], v[30:31], v[184:185] op_sel_hi:[1,0]
	v_pk_mul_f32 v[194:195], v[24:25], v[184:185] op_sel_hi:[1,0]
	v_pk_mul_f32 v[196:197], v[26:27], v[184:185] op_sel_hi:[1,0]
	v_exp_f32_e32 v190, v190
	v_exp_f32_e32 v191, v191
	v_exp_f32_e32 v192, v192
	v_exp_f32_e32 v193, v193
	v_exp_f32_e32 v194, v194
	v_exp_f32_e32 v195, v195
	v_exp_f32_e32 v196, v196
	v_exp_f32_e32 v197, v197
	s_nop 0
	v_pk_add_f32 v[190:191], v[190:191], v[188:189]
	v_pk_add_f32 v[192:193], v[192:193], v[188:189]
	v_pk_add_f32 v[194:195], v[194:195], v[188:189]
	v_pk_add_f32 v[196:197], v[196:197], v[188:189]
	v_rcp_f32_e32 v190, v190
	v_rcp_f32_e32 v191, v191
	v_rcp_f32_e32 v192, v192
	v_rcp_f32_e32 v193, v193
	v_rcp_f32_e32 v194, v194
	v_rcp_f32_e32 v195, v195
	v_rcp_f32_e32 v196, v196
	v_rcp_f32_e32 v197, v197
	s_nop 0
	v_cvt_pk_bf16_f32 v212, v190, v191
	v_cvt_pk_bf16_f32 v213, v192, v193
	v_cvt_pk_bf16_f32 v214, v194, v195
	v_cvt_pk_bf16_f32 v215, v196, v197
	flat_store_dwordx4 v[172:173], v[212:215] offset:256
	v_fmamk_f32 v206, v253, 0x3a800000, v237
	v_rsq_f32_e32 v182, v206
	v_add_u32_e32 v207, 0xa0, v164
	v_mad_i64_i32 v[172:173], s[98:99], s82, v207, 0
	v_lshl_add_u64 v[172:173], v[172:173], 1, s[84:85]
	v_lshl_add_u64 v[172:173], s[62:63], 1, v[172:173]
	v_lshl_add_u64 v[172:173], v[148:149], 1, v[172:173]
	v_mul_f32_e32 v184, 0xbfb8aa3b, v182
	v_pk_mul_f32 v[190:191], v[36:37], v[184:185] op_sel_hi:[1,0]
	v_pk_mul_f32 v[192:193], v[38:39], v[184:185] op_sel_hi:[1,0]
	v_pk_mul_f32 v[194:195], v[32:33], v[184:185] op_sel_hi:[1,0]
	v_pk_mul_f32 v[196:197], v[34:35], v[184:185] op_sel_hi:[1,0]
	v_exp_f32_e32 v190, v190
	v_exp_f32_e32 v191, v191
	v_exp_f32_e32 v192, v192
	v_exp_f32_e32 v193, v193
	v_exp_f32_e32 v194, v194
	v_exp_f32_e32 v195, v195
	v_exp_f32_e32 v196, v196
	v_exp_f32_e32 v197, v197
	s_nop 0
	v_pk_add_f32 v[190:191], v[190:191], v[188:189]
	v_pk_add_f32 v[192:193], v[192:193], v[188:189]
	v_pk_add_f32 v[194:195], v[194:195], v[188:189]
	v_pk_add_f32 v[196:197], v[196:197], v[188:189]
; __device__ __forceinline__ float sigm_f(float v) { return __builtin_amdgcn_rcpf(1.0f + __builtin_amdgcn_exp2f(-1.44269504f * v)); }
; __device__ __forceinline__ float silu_f(float v) { return v * sigm_f(v); }
;     __device__ __forceinline__ void operator()(const f32x4 (&acc)[2][2][4][2], const Unit& u, int wr, int wc, int fr, int fq) const {
;     ...
; #pragma unroll
;                 for (int ai = 0; ai < 2; ++ai)
; #pragma unroll
;                     for (int m = 0; m < 4; ++m) { const int row = row0 + ai * HALF + m * 16; const float rsv = __builtin_amdgcn_rsqf(rs[row] * (1.0f / 1024.0f) + 1e-6f);
;                         bf16_t* rowp = O + (size_t)row * ldc + u.pn * BM + cw;
; #pragma unroll
;                         for (int bj = 0; bj < 2; ++bj) { f32x4 v0 = acc[ai][bj][m][0] * rsv, v1 = acc[ai][bj][m][1] * rsv;
;                             if (sub == 1) {
; #pragma unroll
;                                 for (int e = 0; e < 4; ++e) { v0[e] = silu_f(v0[e]); v1[e] = silu_f(v1[e]); } }
;                             else if (sub == 3) {
; #pragma unroll
;                                 for (int e = 0; e < 4; ++e) { v0[e] = sigm_f(v0[e]); v1[e] = sigm_f(v1[e]); } }
;                             store8(rowp + bj * HALF, v0, v1); } }
	v_rcp_f32_e32 v190, v190
	v_rcp_f32_e32 v191, v191
	v_rcp_f32_e32 v192, v192
	v_rcp_f32_e32 v193, v193
	v_rcp_f32_e32 v194, v194
	v_rcp_f32_e32 v195, v195
	v_rcp_f32_e32 v196, v196
	v_rcp_f32_e32 v197, v197
	s_nop 0
	v_cvt_pk_bf16_f32 v134, v190, v191
	v_cvt_pk_bf16_f32 v135, v192, v193
	v_cvt_pk_bf16_f32 v136, v194, v195
	v_cvt_pk_bf16_f32 v137, v196, v197
	flat_store_dwordx4 v[172:173], v[134:137]
	v_pk_mul_f32 v[190:191], v[12:13], v[184:185] op_sel_hi:[1,0]
	v_pk_mul_f32 v[192:193], v[14:15], v[184:185] op_sel_hi:[1,0]
	v_pk_mul_f32 v[194:195], v[8:9], v[184:185] op_sel_hi:[1,0]
	v_pk_mul_f32 v[196:197], v[10:11], v[184:185] op_sel_hi:[1,0]
	v_exp_f32_e32 v190, v190
	v_exp_f32_e32 v191, v191
	v_exp_f32_e32 v192, v192
	v_exp_f32_e32 v193, v193
	v_exp_f32_e32 v194, v194
	v_exp_f32_e32 v195, v195
	v_exp_f32_e32 v196, v196
	v_exp_f32_e32 v197, v197
	s_nop 0
	v_pk_add_f32 v[190:191], v[190:191], v[188:189]
	v_pk_add_f32 v[192:193], v[192:193], v[188:189]
	v_pk_add_f32 v[194:195], v[194:195], v[188:189]
	v_pk_add_f32 v[196:197], v[196:197], v[188:189]
	v_rcp_f32_e32 v190, v190
	v_rcp_f32_e32 v191, v191
	v_rcp_f32_e32 v192, v192
	v_rcp_f32_e32 v193, v193
	v_rcp_f32_e32 v194, v194
	v_rcp_f32_e32 v195, v195
	v_rcp_f32_e32 v196, v196
	v_rcp_f32_e32 v197, v197
	s_nop 0
	v_cvt_pk_bf16_f32 v212, v190, v191
	v_cvt_pk_bf16_f32 v213, v192, v193
	v_cvt_pk_bf16_f32 v214, v194, v195
	v_cvt_pk_bf16_f32 v215, v196, v197
	flat_store_dwordx4 v[172:173], v[212:215] offset:256
	v_fmamk_f32 v206, v255, 0x3a800000, v237
	v_rsq_f32_e32 v182, v206
	v_add_u32_e32 v207, 0xb0, v164
	v_mad_i64_i32 v[172:173], s[98:99], s82, v207, 0
	v_lshl_add_u64 v[172:173], v[172:173], 1, s[84:85]
	v_lshl_add_u64 v[172:173], s[62:63], 1, v[172:173]
	v_lshl_add_u64 v[172:173], v[148:149], 1, v[172:173]
	v_mul_f32_e32 v184, 0xbfb8aa3b, v182
	v_pk_mul_f32 v[190:191], v[20:21], v[184:185] op_sel_hi:[1,0]
	v_pk_mul_f32 v[192:193], v[22:23], v[184:185] op_sel_hi:[1,0]
	v_pk_mul_f32 v[194:195], v[16:17], v[184:185] op_sel_hi:[1,0]
	v_pk_mul_f32 v[196:197], v[18:19], v[184:185] op_sel_hi:[1,0]
	v_exp_f32_e32 v190, v190
	v_exp_f32_e32 v191, v191
	v_exp_f32_e32 v192, v192
	v_exp_f32_e32 v193, v193
	v_exp_f32_e32 v194, v194
	v_exp_f32_e32 v195, v195
	v_exp_f32_e32 v196, v196
	v_exp_f32_e32 v197, v197
	s_nop 0
	v_pk_add_f32 v[190:191], v[190:191], v[188:189]
	v_pk_add_f32 v[192:193], v[192:193], v[188:189]
	v_pk_add_f32 v[194:195], v[194:195], v[188:189]
	v_pk_add_f32 v[196:197], v[196:197], v[188:189]
	v_rcp_f32_e32 v190, v190
	v_rcp_f32_e32 v191, v191
	v_rcp_f32_e32 v192, v192
	v_rcp_f32_e32 v193, v193
	v_rcp_f32_e32 v194, v194
	v_rcp_f32_e32 v195, v195
	v_rcp_f32_e32 v196, v196
	v_rcp_f32_e32 v197, v197
	s_nop 0
	v_cvt_pk_bf16_f32 v134, v190, v191
	v_cvt_pk_bf16_f32 v135, v192, v193
	v_cvt_pk_bf16_f32 v136, v194, v195
	v_cvt_pk_bf16_f32 v137, v196, v197
	flat_store_dwordx4 v[172:173], v[134:137]
	v_pk_mul_f32 v[190:191], v[4:5], v[184:185] op_sel_hi:[1,0]
	v_pk_mul_f32 v[192:193], v[6:7], v[184:185] op_sel_hi:[1,0]
	v_pk_mul_f32 v[194:195], v[0:1], v[184:185] op_sel_hi:[1,0]
	v_pk_mul_f32 v[196:197], v[2:3], v[184:185] op_sel_hi:[1,0]
	v_exp_f32_e32 v190, v190
	v_exp_f32_e32 v191, v191
	v_exp_f32_e32 v192, v192
	v_exp_f32_e32 v193, v193
	v_exp_f32_e32 v194, v194
	v_exp_f32_e32 v195, v195
	v_exp_f32_e32 v196, v196
	v_exp_f32_e32 v197, v197
	s_nop 0
	v_pk_add_f32 v[190:191], v[190:191], v[188:189]
	v_pk_add_f32 v[192:193], v[192:193], v[188:189]
	v_pk_add_f32 v[194:195], v[194:195], v[188:189]
	v_pk_add_f32 v[196:197], v[196:197], v[188:189]
	v_rcp_f32_e32 v190, v190
	v_rcp_f32_e32 v191, v191
	v_rcp_f32_e32 v192, v192
	v_rcp_f32_e32 v193, v193
	v_rcp_f32_e32 v194, v194
	v_rcp_f32_e32 v195, v195
	v_rcp_f32_e32 v196, v196
	v_rcp_f32_e32 v197, v197
	s_nop 0
	v_cvt_pk_bf16_f32 v212, v190, v191
	v_cvt_pk_bf16_f32 v213, v192, v193
	v_cvt_pk_bf16_f32 v214, v194, v195
	v_cvt_pk_bf16_f32 v215, v196, v197
	flat_store_dwordx4 v[172:173], v[212:215] offset:256
	s_branch .Lmix_done
.Lmix_silu:
	v_mov_b32_e32 v182, v130
	v_mad_i64_i32 v[172:173], s[98:99], s82, v164, 0
	v_lshl_add_u64 v[172:173], v[172:173], 1, s[84:85]
	v_lshl_add_u64 v[172:173], s[62:63], 1, v[172:173]
	v_lshl_add_u64 v[172:173], v[148:149], 1, v[172:173]
	v_mul_f32_e32 v184, 0xbfb8aa3b, v182
	v_pk_mul_f32 v[190:191], v[124:125], v[184:185] op_sel_hi:[1,0]
	v_pk_mul_f32 v[192:193], v[126:127], v[184:185] op_sel_hi:[1,0]
	v_pk_mul_f32 v[194:195], v[120:121], v[184:185] op_sel_hi:[1,0]
	v_pk_mul_f32 v[196:197], v[122:123], v[184:185] op_sel_hi:[1,0]
	v_exp_f32_e32 v190, v190
	v_exp_f32_e32 v191, v191
	v_exp_f32_e32 v192, v192
	v_exp_f32_e32 v193, v193
	v_exp_f32_e32 v194, v194
	v_exp_f32_e32 v195, v195
	v_exp_f32_e32 v196, v196
	v_exp_f32_e32 v197, v197
	v_pk_mul_f32 v[198:199], v[124:125], v[182:183] op_sel_hi:[1,0]
	v_pk_mul_f32 v[200:201], v[126:127], v[182:183] op_sel_hi:[1,0]
	v_pk_mul_f32 v[202:203], v[120:121], v[182:183] op_sel_hi:[1,0]
	v_pk_mul_f32 v[204:205], v[122:123], v[182:183] op_sel_hi:[1,0]
	v_pk_add_f32 v[190:191], v[190:191], v[188:189]
	v_pk_add_f32 v[192:193], v[192:193], v[188:189]
	v_pk_add_f32 v[194:195], v[194:195], v[188:189]
	v_pk_add_f32 v[196:197], v[196:197], v[188:189]
	v_rcp_f32_e32 v190, v190
	v_rcp_f32_e32 v191, v191
	v_rcp_f32_e32 v192, v192
	v_rcp_f32_e32 v193, v193
	v_rcp_f32_e32 v194, v194
	v_rcp_f32_e32 v195, v195
	v_rcp_f32_e32 v196, v196
	v_rcp_f32_e32 v197, v197
	v_pk_mul_f32 v[198:199], v[198:199], v[190:191]
	v_pk_mul_f32 v[200:201], v[200:201], v[192:193]
	v_pk_mul_f32 v[202:203], v[202:203], v[194:195]
	v_pk_mul_f32 v[204:205], v[204:205], v[196:197]
	v_cvt_pk_bf16_f32 v134, v198, v199
; __device__ __forceinline__ float sigm_f(float v) { return __builtin_amdgcn_rcpf(1.0f + __builtin_amdgcn_exp2f(-1.44269504f * v)); }
; __device__ __forceinline__ float silu_f(float v) { return v * sigm_f(v); }
;     __device__ __forceinline__ void operator()(const f32x4 (&acc)[2][2][4][2], const Unit& u, int wr, int wc, int fr, int fq) const {
;     ...
; #pragma unroll
;                 for (int ai = 0; ai < 2; ++ai)
; #pragma unroll
;                     for (int m = 0; m < 4; ++m) { const int row = row0 + ai * HALF + m * 16; const float rsv = __builtin_amdgcn_rsqf(rs[row] * (1.0f / 1024.0f) + 1e-6f);
;                         bf16_t* rowp = O + (size_t)row * ldc + u.pn * BM + cw;
; #pragma unroll
;                         for (int bj = 0; bj < 2; ++bj) { f32x4 v0 = acc[ai][bj][m][0] * rsv, v1 = acc[ai][bj][m][1] * rsv;
;                             if (sub == 1) {
; #pragma unroll
;                                 for (int e = 0; e < 4; ++e) { v0[e] = silu_f(v0[e]); v1[e] = silu_f(v1[e]); } }
;                             else if (sub == 3) {
; #pragma unroll
;                                 for (int e = 0; e < 4; ++e) { v0[e] = sigm_f(v0[e]); v1[e] = sigm_f(v1[e]); } }
;                             store8(rowp + bj * HALF, v0, v1); } }
	v_cvt_pk_bf16_f32 v135, v200, v201
	v_cvt_pk_bf16_f32 v136, v202, v203
	v_cvt_pk_bf16_f32 v137, v204, v205
	flat_store_dwordx4 v[172:173], v[134:137]
	v_pk_mul_f32 v[190:191], v[108:109], v[184:185] op_sel_hi:[1,0]
	v_pk_mul_f32 v[192:193], v[110:111], v[184:185] op_sel_hi:[1,0]
	v_pk_mul_f32 v[194:195], v[104:105], v[184:185] op_sel_hi:[1,0]
	v_pk_mul_f32 v[196:197], v[106:107], v[184:185] op_sel_hi:[1,0]
	v_exp_f32_e32 v190, v190
	v_exp_f32_e32 v191, v191
	v_exp_f32_e32 v192, v192
	v_exp_f32_e32 v193, v193
	v_exp_f32_e32 v194, v194
	v_exp_f32_e32 v195, v195
	v_exp_f32_e32 v196, v196
	v_exp_f32_e32 v197, v197
	v_pk_mul_f32 v[198:199], v[108:109], v[182:183] op_sel_hi:[1,0]
	v_pk_mul_f32 v[200:201], v[110:111], v[182:183] op_sel_hi:[1,0]
	v_pk_mul_f32 v[202:203], v[104:105], v[182:183] op_sel_hi:[1,0]
	v_pk_mul_f32 v[204:205], v[106:107], v[182:183] op_sel_hi:[1,0]
	v_pk_add_f32 v[190:191], v[190:191], v[188:189]
	v_pk_add_f32 v[192:193], v[192:193], v[188:189]
	v_pk_add_f32 v[194:195], v[194:195], v[188:189]
	v_pk_add_f32 v[196:197], v[196:197], v[188:189]
	v_rcp_f32_e32 v190, v190
	v_rcp_f32_e32 v191, v191
	v_rcp_f32_e32 v192, v192
	v_rcp_f32_e32 v193, v193
	v_rcp_f32_e32 v194, v194
	v_rcp_f32_e32 v195, v195
	v_rcp_f32_e32 v196, v196
	v_rcp_f32_e32 v197, v197
	v_pk_mul_f32 v[198:199], v[198:199], v[190:191]
	v_pk_mul_f32 v[200:201], v[200:201], v[192:193]
	v_pk_mul_f32 v[202:203], v[202:203], v[194:195]
	v_pk_mul_f32 v[204:205], v[204:205], v[196:197]
	v_cvt_pk_bf16_f32 v212, v198, v199
	v_cvt_pk_bf16_f32 v213, v200, v201
	v_cvt_pk_bf16_f32 v214, v202, v203
	v_cvt_pk_bf16_f32 v215, v204, v205
	flat_store_dwordx4 v[172:173], v[212:215] offset:256
	v_fmamk_f32 v206, v247, 0x3a800000, v237
	v_rsq_f32_e32 v182, v206
	v_add_u32_e32 v207, 0x10, v164
	v_mad_i64_i32 v[172:173], s[98:99], s82, v207, 0
	v_lshl_add_u64 v[172:173], v[172:173], 1, s[84:85]
	v_lshl_add_u64 v[172:173], s[62:63], 1, v[172:173]
	v_lshl_add_u64 v[172:173], v[148:149], 1, v[172:173]
	v_mul_f32_e32 v184, 0xbfb8aa3b, v182
	v_pk_mul_f32 v[190:191], v[116:117], v[184:185] op_sel_hi:[1,0]
	v_pk_mul_f32 v[192:193], v[118:119], v[184:185] op_sel_hi:[1,0]
	v_pk_mul_f32 v[194:195], v[112:113], v[184:185] op_sel_hi:[1,0]
	v_pk_mul_f32 v[196:197], v[114:115], v[184:185] op_sel_hi:[1,0]
	v_exp_f32_e32 v190, v190
	v_exp_f32_e32 v191, v191
	v_exp_f32_e32 v192, v192
	v_exp_f32_e32 v193, v193
	v_exp_f32_e32 v194, v194
	v_exp_f32_e32 v195, v195
	v_exp_f32_e32 v196, v196
	v_exp_f32_e32 v197, v197
	v_pk_mul_f32 v[198:199], v[116:117], v[182:183] op_sel_hi:[1,0]
	v_pk_mul_f32 v[200:201], v[118:119], v[182:183] op_sel_hi:[1,0]
	v_pk_mul_f32 v[202:203], v[112:113], v[182:183] op_sel_hi:[1,0]
	v_pk_mul_f32 v[204:205], v[114:115], v[182:183] op_sel_hi:[1,0]
	v_pk_add_f32 v[190:191], v[190:191], v[188:189]
	v_pk_add_f32 v[192:193], v[192:193], v[188:189]
	v_pk_add_f32 v[194:195], v[194:195], v[188:189]
	v_pk_add_f32 v[196:197], v[196:197], v[188:189]
	v_rcp_f32_e32 v190, v190
	v_rcp_f32_e32 v191, v191
	v_rcp_f32_e32 v192, v192
	v_rcp_f32_e32 v193, v193
	v_rcp_f32_e32 v194, v194
	v_rcp_f32_e32 v195, v195
	v_rcp_f32_e32 v196, v196
	v_rcp_f32_e32 v197, v197
	v_pk_mul_f32 v[198:199], v[198:199], v[190:191]
	v_pk_mul_f32 v[200:201], v[200:201], v[192:193]
	v_pk_mul_f32 v[202:203], v[202:203], v[194:195]
	v_pk_mul_f32 v[204:205], v[204:205], v[196:197]
	v_cvt_pk_bf16_f32 v134, v198, v199
	v_cvt_pk_bf16_f32 v135, v200, v201
	v_cvt_pk_bf16_f32 v136, v202, v203
	v_cvt_pk_bf16_f32 v137, v204, v205
	flat_store_dwordx4 v[172:173], v[134:137]
	v_pk_mul_f32 v[190:191], v[92:93], v[184:185] op_sel_hi:[1,0]
	v_pk_mul_f32 v[192:193], v[94:95], v[184:185] op_sel_hi:[1,0]
	v_pk_mul_f32 v[194:195], v[88:89], v[184:185] op_sel_hi:[1,0]
	v_pk_mul_f32 v[196:197], v[90:91], v[184:185] op_sel_hi:[1,0]
	v_exp_f32_e32 v190, v190
	v_exp_f32_e32 v191, v191
	v_exp_f32_e32 v192, v192
	v_exp_f32_e32 v193, v193
	v_exp_f32_e32 v194, v194
	v_exp_f32_e32 v195, v195
	v_exp_f32_e32 v196, v196
	v_exp_f32_e32 v197, v197
	v_pk_mul_f32 v[198:199], v[92:93], v[182:183] op_sel_hi:[1,0]
	v_pk_mul_f32 v[200:201], v[94:95], v[182:183] op_sel_hi:[1,0]
	v_pk_mul_f32 v[202:203], v[88:89], v[182:183] op_sel_hi:[1,0]
	v_pk_mul_f32 v[204:205], v[90:91], v[182:183] op_sel_hi:[1,0]
	v_pk_add_f32 v[190:191], v[190:191], v[188:189]
	v_pk_add_f32 v[192:193], v[192:193], v[188:189]
	v_pk_add_f32 v[194:195], v[194:195], v[188:189]
	v_pk_add_f32 v[196:197], v[196:197], v[188:189]
	v_rcp_f32_e32 v190, v190
	v_rcp_f32_e32 v191, v191
	v_rcp_f32_e32 v192, v192
	v_rcp_f32_e32 v193, v193
	v_rcp_f32_e32 v194, v194
	v_rcp_f32_e32 v195, v195
	v_rcp_f32_e32 v196, v196
	v_rcp_f32_e32 v197, v197
	v_pk_mul_f32 v[198:199], v[198:199], v[190:191]
	v_pk_mul_f32 v[200:201], v[200:201], v[192:193]
	v_pk_mul_f32 v[202:203], v[202:203], v[194:195]
	v_pk_mul_f32 v[204:205], v[204:205], v[196:197]
	v_cvt_pk_bf16_f32 v212, v198, v199
	v_cvt_pk_bf16_f32 v213, v200, v201
	v_cvt_pk_bf16_f32 v214, v202, v203
	v_cvt_pk_bf16_f32 v215, v204, v205
	flat_store_dwordx4 v[172:173], v[212:215] offset:256
	v_fmamk_f32 v206, v248, 0x3a800000, v237
	v_rsq_f32_e32 v182, v206
	v_add_u32_e32 v207, 0x20, v164
	v_mad_i64_i32 v[172:173], s[98:99], s82, v207, 0
	v_lshl_add_u64 v[172:173], v[172:173], 1, s[84:85]
	v_lshl_add_u64 v[172:173], s[62:63], 1, v[172:173]
	v_lshl_add_u64 v[172:173], v[148:149], 1, v[172:173]
	v_mul_f32_e32 v184, 0xbfb8aa3b, v182
	v_pk_mul_f32 v[190:191], v[100:101], v[184:185] op_sel_hi:[1,0]
	v_pk_mul_f32 v[192:193], v[102:103], v[184:185] op_sel_hi:[1,0]
	v_pk_mul_f32 v[194:195], v[96:97], v[184:185] op_sel_hi:[1,0]
	v_pk_mul_f32 v[196:197], v[98:99], v[184:185] op_sel_hi:[1,0]
; __device__ __forceinline__ float sigm_f(float v) { return __builtin_amdgcn_rcpf(1.0f + __builtin_amdgcn_exp2f(-1.44269504f * v)); }
; __device__ __forceinline__ float silu_f(float v) { return v * sigm_f(v); }
;     __device__ __forceinline__ void operator()(const f32x4 (&acc)[2][2][4][2], const Unit& u, int wr, int wc, int fr, int fq) const {
;     ...
; #pragma unroll
;                 for (int ai = 0; ai < 2; ++ai)
; #pragma unroll
;                     for (int m = 0; m < 4; ++m) { const int row = row0 + ai * HALF + m * 16; const float rsv = __builtin_amdgcn_rsqf(rs[row] * (1.0f / 1024.0f) + 1e-6f);
;                         bf16_t* rowp = O + (size_t)row * ldc + u.pn * BM + cw;
; #pragma unroll
;                         for (int bj = 0; bj < 2; ++bj) { f32x4 v0 = acc[ai][bj][m][0] * rsv, v1 = acc[ai][bj][m][1] * rsv;
;                             if (sub == 1) {
; #pragma unroll
;                                 for (int e = 0; e < 4; ++e) { v0[e] = silu_f(v0[e]); v1[e] = silu_f(v1[e]); } }
;                             else if (sub == 3) {
; #pragma unroll
;                                 for (int e = 0; e < 4; ++e) { v0[e] = sigm_f(v0[e]); v1[e] = sigm_f(v1[e]); } }
;                             store8(rowp + bj * HALF, v0, v1); } }
	v_exp_f32_e32 v190, v190
	v_exp_f32_e32 v191, v191
	v_exp_f32_e32 v192, v192
	v_exp_f32_e32 v193, v193
	v_exp_f32_e32 v194, v194
	v_exp_f32_e32 v195, v195
	v_exp_f32_e32 v196, v196
	v_exp_f32_e32 v197, v197
	v_pk_mul_f32 v[198:199], v[100:101], v[182:183] op_sel_hi:[1,0]
	v_pk_mul_f32 v[200:201], v[102:103], v[182:183] op_sel_hi:[1,0]
	v_pk_mul_f32 v[202:203], v[96:97], v[182:183] op_sel_hi:[1,0]
	v_pk_mul_f32 v[204:205], v[98:99], v[182:183] op_sel_hi:[1,0]
	v_pk_add_f32 v[190:191], v[190:191], v[188:189]
	v_pk_add_f32 v[192:193], v[192:193], v[188:189]
	v_pk_add_f32 v[194:195], v[194:195], v[188:189]
	v_pk_add_f32 v[196:197], v[196:197], v[188:189]
	v_rcp_f32_e32 v190, v190
	v_rcp_f32_e32 v191, v191
	v_rcp_f32_e32 v192, v192
	v_rcp_f32_e32 v193, v193
	v_rcp_f32_e32 v194, v194
	v_rcp_f32_e32 v195, v195
	v_rcp_f32_e32 v196, v196
	v_rcp_f32_e32 v197, v197
	v_pk_mul_f32 v[198:199], v[198:199], v[190:191]
	v_pk_mul_f32 v[200:201], v[200:201], v[192:193]
	v_pk_mul_f32 v[202:203], v[202:203], v[194:195]
	v_pk_mul_f32 v[204:205], v[204:205], v[196:197]
	v_cvt_pk_bf16_f32 v134, v198, v199
	v_cvt_pk_bf16_f32 v135, v200, v201
	v_cvt_pk_bf16_f32 v136, v202, v203
	v_cvt_pk_bf16_f32 v137, v204, v205
	flat_store_dwordx4 v[172:173], v[134:137]
	v_pk_mul_f32 v[190:191], v[76:77], v[184:185] op_sel_hi:[1,0]
	v_pk_mul_f32 v[192:193], v[78:79], v[184:185] op_sel_hi:[1,0]
	v_pk_mul_f32 v[194:195], v[72:73], v[184:185] op_sel_hi:[1,0]
	v_pk_mul_f32 v[196:197], v[74:75], v[184:185] op_sel_hi:[1,0]
	v_exp_f32_e32 v190, v190
	v_exp_f32_e32 v191, v191
	v_exp_f32_e32 v192, v192
	v_exp_f32_e32 v193, v193
	v_exp_f32_e32 v194, v194
	v_exp_f32_e32 v195, v195
	v_exp_f32_e32 v196, v196
	v_exp_f32_e32 v197, v197
	v_pk_mul_f32 v[198:199], v[76:77], v[182:183] op_sel_hi:[1,0]
	v_pk_mul_f32 v[200:201], v[78:79], v[182:183] op_sel_hi:[1,0]
	v_pk_mul_f32 v[202:203], v[72:73], v[182:183] op_sel_hi:[1,0]
	v_pk_mul_f32 v[204:205], v[74:75], v[182:183] op_sel_hi:[1,0]
	v_pk_add_f32 v[190:191], v[190:191], v[188:189]
	v_pk_add_f32 v[192:193], v[192:193], v[188:189]
	v_pk_add_f32 v[194:195], v[194:195], v[188:189]
	v_pk_add_f32 v[196:197], v[196:197], v[188:189]
	v_rcp_f32_e32 v190, v190
	v_rcp_f32_e32 v191, v191
	v_rcp_f32_e32 v192, v192
	v_rcp_f32_e32 v193, v193
	v_rcp_f32_e32 v194, v194
	v_rcp_f32_e32 v195, v195
	v_rcp_f32_e32 v196, v196
	v_rcp_f32_e32 v197, v197
	v_pk_mul_f32 v[198:199], v[198:199], v[190:191]
	v_pk_mul_f32 v[200:201], v[200:201], v[192:193]
	v_pk_mul_f32 v[202:203], v[202:203], v[194:195]
	v_pk_mul_f32 v[204:205], v[204:205], v[196:197]
	v_cvt_pk_bf16_f32 v212, v198, v199
	v_cvt_pk_bf16_f32 v213, v200, v201
	v_cvt_pk_bf16_f32 v214, v202, v203
	v_cvt_pk_bf16_f32 v215, v204, v205
	flat_store_dwordx4 v[172:173], v[212:215] offset:256
	v_fmamk_f32 v206, v249, 0x3a800000, v237
	v_rsq_f32_e32 v182, v206
	v_add_u32_e32 v207, 0x30, v164
	v_mad_i64_i32 v[172:173], s[98:99], s82, v207, 0
	v_lshl_add_u64 v[172:173], v[172:173], 1, s[84:85]
	v_lshl_add_u64 v[172:173], s[62:63], 1, v[172:173]
	v_lshl_add_u64 v[172:173], v[148:149], 1, v[172:173]
	v_mul_f32_e32 v184, 0xbfb8aa3b, v182
	v_pk_mul_f32 v[190:191], v[84:85], v[184:185] op_sel_hi:[1,0]
	v_pk_mul_f32 v[192:193], v[86:87], v[184:185] op_sel_hi:[1,0]
	v_pk_mul_f32 v[194:195], v[80:81], v[184:185] op_sel_hi:[1,0]
	v_pk_mul_f32 v[196:197], v[82:83], v[184:185] op_sel_hi:[1,0]
	v_exp_f32_e32 v190, v190
	v_exp_f32_e32 v191, v191
	v_exp_f32_e32 v192, v192
	v_exp_f32_e32 v193, v193
	v_exp_f32_e32 v194, v194
	v_exp_f32_e32 v195, v195
	v_exp_f32_e32 v196, v196
	v_exp_f32_e32 v197, v197
	v_pk_mul_f32 v[198:199], v[84:85], v[182:183] op_sel_hi:[1,0]
	v_pk_mul_f32 v[200:201], v[86:87], v[182:183] op_sel_hi:[1,0]
	v_pk_mul_f32 v[202:203], v[80:81], v[182:183] op_sel_hi:[1,0]
	v_pk_mul_f32 v[204:205], v[82:83], v[182:183] op_sel_hi:[1,0]
	v_pk_add_f32 v[190:191], v[190:191], v[188:189]
	v_pk_add_f32 v[192:193], v[192:193], v[188:189]
	v_pk_add_f32 v[194:195], v[194:195], v[188:189]
	v_pk_add_f32 v[196:197], v[196:197], v[188:189]
	v_rcp_f32_e32 v190, v190
	v_rcp_f32_e32 v191, v191
	v_rcp_f32_e32 v192, v192
	v_rcp_f32_e32 v193, v193
	v_rcp_f32_e32 v194, v194
	v_rcp_f32_e32 v195, v195
	v_rcp_f32_e32 v196, v196
	v_rcp_f32_e32 v197, v197
	v_pk_mul_f32 v[198:199], v[198:199], v[190:191]
	v_pk_mul_f32 v[200:201], v[200:201], v[192:193]
	v_pk_mul_f32 v[202:203], v[202:203], v[194:195]
	v_pk_mul_f32 v[204:205], v[204:205], v[196:197]
	v_cvt_pk_bf16_f32 v134, v198, v199
	v_cvt_pk_bf16_f32 v135, v200, v201
	v_cvt_pk_bf16_f32 v136, v202, v203
	v_cvt_pk_bf16_f32 v137, v204, v205
	flat_store_dwordx4 v[172:173], v[134:137]
	v_pk_mul_f32 v[190:191], v[68:69], v[184:185] op_sel_hi:[1,0]
	v_pk_mul_f32 v[192:193], v[70:71], v[184:185] op_sel_hi:[1,0]
	v_pk_mul_f32 v[194:195], v[64:65], v[184:185] op_sel_hi:[1,0]
	v_pk_mul_f32 v[196:197], v[66:67], v[184:185] op_sel_hi:[1,0]
	v_exp_f32_e32 v190, v190
	v_exp_f32_e32 v191, v191
	v_exp_f32_e32 v192, v192
	v_exp_f32_e32 v193, v193
	v_exp_f32_e32 v194, v194
	v_exp_f32_e32 v195, v195
	v_exp_f32_e32 v196, v196
	v_exp_f32_e32 v197, v197
	v_pk_mul_f32 v[198:199], v[68:69], v[182:183] op_sel_hi:[1,0]
	v_pk_mul_f32 v[200:201], v[70:71], v[182:183] op_sel_hi:[1,0]
	v_pk_mul_f32 v[202:203], v[64:65], v[182:183] op_sel_hi:[1,0]
	v_pk_mul_f32 v[204:205], v[66:67], v[182:183] op_sel_hi:[1,0]
	v_pk_add_f32 v[190:191], v[190:191], v[188:189]
	v_pk_add_f32 v[192:193], v[192:193], v[188:189]
	v_pk_add_f32 v[194:195], v[194:195], v[188:189]
	v_pk_add_f32 v[196:197], v[196:197], v[188:189]
	v_rcp_f32_e32 v190, v190
	v_rcp_f32_e32 v191, v191
	v_rcp_f32_e32 v192, v192
	v_rcp_f32_e32 v193, v193
	v_rcp_f32_e32 v194, v194
; __device__ __forceinline__ float sigm_f(float v) { return __builtin_amdgcn_rcpf(1.0f + __builtin_amdgcn_exp2f(-1.44269504f * v)); }
; __device__ __forceinline__ float silu_f(float v) { return v * sigm_f(v); }
;     __device__ __forceinline__ void operator()(const f32x4 (&acc)[2][2][4][2], const Unit& u, int wr, int wc, int fr, int fq) const {
;     ...
; #pragma unroll
;                 for (int ai = 0; ai < 2; ++ai)
; #pragma unroll
;                     for (int m = 0; m < 4; ++m) { const int row = row0 + ai * HALF + m * 16; const float rsv = __builtin_amdgcn_rsqf(rs[row] * (1.0f / 1024.0f) + 1e-6f);
;                         bf16_t* rowp = O + (size_t)row * ldc + u.pn * BM + cw;
; #pragma unroll
;                         for (int bj = 0; bj < 2; ++bj) { f32x4 v0 = acc[ai][bj][m][0] * rsv, v1 = acc[ai][bj][m][1] * rsv;
;                             if (sub == 1) {
; #pragma unroll
;                                 for (int e = 0; e < 4; ++e) { v0[e] = silu_f(v0[e]); v1[e] = silu_f(v1[e]); } }
;                             else if (sub == 3) {
; #pragma unroll
;                                 for (int e = 0; e < 4; ++e) { v0[e] = sigm_f(v0[e]); v1[e] = sigm_f(v1[e]); } }
;                             store8(rowp + bj * HALF, v0, v1); } }
	v_rcp_f32_e32 v195, v195
	v_rcp_f32_e32 v196, v196
	v_rcp_f32_e32 v197, v197
	v_pk_mul_f32 v[198:199], v[198:199], v[190:191]
	v_pk_mul_f32 v[200:201], v[200:201], v[192:193]
	v_pk_mul_f32 v[202:203], v[202:203], v[194:195]
	v_pk_mul_f32 v[204:205], v[204:205], v[196:197]
	v_cvt_pk_bf16_f32 v212, v198, v199
	v_cvt_pk_bf16_f32 v213, v200, v201
	v_cvt_pk_bf16_f32 v214, v202, v203
	v_cvt_pk_bf16_f32 v215, v204, v205
	flat_store_dwordx4 v[172:173], v[212:215] offset:256
	v_fmamk_f32 v206, v250, 0x3a800000, v237
	v_rsq_f32_e32 v182, v206
	v_add_u32_e32 v207, 0x80, v164
	v_mad_i64_i32 v[172:173], s[98:99], s82, v207, 0
	v_lshl_add_u64 v[172:173], v[172:173], 1, s[84:85]
	v_lshl_add_u64 v[172:173], s[62:63], 1, v[172:173]
	v_lshl_add_u64 v[172:173], v[148:149], 1, v[172:173]
	v_mul_f32_e32 v184, 0xbfb8aa3b, v182
	v_pk_mul_f32 v[190:191], v[60:61], v[184:185] op_sel_hi:[1,0]
	v_pk_mul_f32 v[192:193], v[62:63], v[184:185] op_sel_hi:[1,0]
	v_pk_mul_f32 v[194:195], v[56:57], v[184:185] op_sel_hi:[1,0]
	v_pk_mul_f32 v[196:197], v[58:59], v[184:185] op_sel_hi:[1,0]
	v_exp_f32_e32 v190, v190
	v_exp_f32_e32 v191, v191
	v_exp_f32_e32 v192, v192
	v_exp_f32_e32 v193, v193
	v_exp_f32_e32 v194, v194
	v_exp_f32_e32 v195, v195
	v_exp_f32_e32 v196, v196
	v_exp_f32_e32 v197, v197
	v_pk_mul_f32 v[198:199], v[60:61], v[182:183] op_sel_hi:[1,0]
	v_pk_mul_f32 v[200:201], v[62:63], v[182:183] op_sel_hi:[1,0]
	v_pk_mul_f32 v[202:203], v[56:57], v[182:183] op_sel_hi:[1,0]
	v_pk_mul_f32 v[204:205], v[58:59], v[182:183] op_sel_hi:[1,0]
	v_pk_add_f32 v[190:191], v[190:191], v[188:189]
	v_pk_add_f32 v[192:193], v[192:193], v[188:189]
	v_pk_add_f32 v[194:195], v[194:195], v[188:189]
	v_pk_add_f32 v[196:197], v[196:197], v[188:189]
	v_rcp_f32_e32 v190, v190
	v_rcp_f32_e32 v191, v191
	v_rcp_f32_e32 v192, v192
	v_rcp_f32_e32 v193, v193
	v_rcp_f32_e32 v194, v194
	v_rcp_f32_e32 v195, v195
	v_rcp_f32_e32 v196, v196
	v_rcp_f32_e32 v197, v197
	v_pk_mul_f32 v[198:199], v[198:199], v[190:191]
	v_pk_mul_f32 v[200:201], v[200:201], v[192:193]
	v_pk_mul_f32 v[202:203], v[202:203], v[194:195]
	v_pk_mul_f32 v[204:205], v[204:205], v[196:197]
	v_cvt_pk_bf16_f32 v134, v198, v199
	v_cvt_pk_bf16_f32 v135, v200, v201
	v_cvt_pk_bf16_f32 v136, v202, v203
	v_cvt_pk_bf16_f32 v137, v204, v205
	flat_store_dwordx4 v[172:173], v[134:137]
	v_pk_mul_f32 v[190:191], v[44:45], v[184:185] op_sel_hi:[1,0]
	v_pk_mul_f32 v[192:193], v[46:47], v[184:185] op_sel_hi:[1,0]
	v_pk_mul_f32 v[194:195], v[40:41], v[184:185] op_sel_hi:[1,0]
	v_pk_mul_f32 v[196:197], v[42:43], v[184:185] op_sel_hi:[1,0]
	v_exp_f32_e32 v190, v190
	v_exp_f32_e32 v191, v191
	v_exp_f32_e32 v192, v192
	v_exp_f32_e32 v193, v193
	v_exp_f32_e32 v194, v194
	v_exp_f32_e32 v195, v195
	v_exp_f32_e32 v196, v196
	v_exp_f32_e32 v197, v197
	v_pk_mul_f32 v[198:199], v[44:45], v[182:183] op_sel_hi:[1,0]
	v_pk_mul_f32 v[200:201], v[46:47], v[182:183] op_sel_hi:[1,0]
	v_pk_mul_f32 v[202:203], v[40:41], v[182:183] op_sel_hi:[1,0]
	v_pk_mul_f32 v[204:205], v[42:43], v[182:183] op_sel_hi:[1,0]
	v_pk_add_f32 v[190:191], v[190:191], v[188:189]
	v_pk_add_f32 v[192:193], v[192:193], v[188:189]
	v_pk_add_f32 v[194:195], v[194:195], v[188:189]
	v_pk_add_f32 v[196:197], v[196:197], v[188:189]
	v_rcp_f32_e32 v190, v190
	v_rcp_f32_e32 v191, v191
	v_rcp_f32_e32 v192, v192
	v_rcp_f32_e32 v193, v193
	v_rcp_f32_e32 v194, v194
	v_rcp_f32_e32 v195, v195
	v_rcp_f32_e32 v196, v196
	v_rcp_f32_e32 v197, v197
	v_pk_mul_f32 v[198:199], v[198:199], v[190:191]
	v_pk_mul_f32 v[200:201], v[200:201], v[192:193]
	v_pk_mul_f32 v[202:203], v[202:203], v[194:195]
	v_pk_mul_f32 v[204:205], v[204:205], v[196:197]
	v_cvt_pk_bf16_f32 v212, v198, v199
	v_cvt_pk_bf16_f32 v213, v200, v201
	v_cvt_pk_bf16_f32 v214, v202, v203
	v_cvt_pk_bf16_f32 v215, v204, v205
	flat_store_dwordx4 v[172:173], v[212:215] offset:256
	v_fmamk_f32 v206, v252, 0x3a800000, v237
	v_rsq_f32_e32 v182, v206
	v_add_u32_e32 v207, 0x90, v164
	v_mad_i64_i32 v[172:173], s[98:99], s82, v207, 0
	v_lshl_add_u64 v[172:173], v[172:173], 1, s[84:85]
	v_lshl_add_u64 v[172:173], s[62:63], 1, v[172:173]
	v_lshl_add_u64 v[172:173], v[148:149], 1, v[172:173]
	v_mul_f32_e32 v184, 0xbfb8aa3b, v182
	v_pk_mul_f32 v[190:191], v[52:53], v[184:185] op_sel_hi:[1,0]
	v_pk_mul_f32 v[192:193], v[54:55], v[184:185] op_sel_hi:[1,0]
	v_pk_mul_f32 v[194:195], v[48:49], v[184:185] op_sel_hi:[1,0]
	v_pk_mul_f32 v[196:197], v[50:51], v[184:185] op_sel_hi:[1,0]
	v_exp_f32_e32 v190, v190
	v_exp_f32_e32 v191, v191
	v_exp_f32_e32 v192, v192
	v_exp_f32_e32 v193, v193
	v_exp_f32_e32 v194, v194
	v_exp_f32_e32 v195, v195
	v_exp_f32_e32 v196, v196
	v_exp_f32_e32 v197, v197
	v_pk_mul_f32 v[198:199], v[52:53], v[182:183] op_sel_hi:[1,0]
	v_pk_mul_f32 v[200:201], v[54:55], v[182:183] op_sel_hi:[1,0]
	v_pk_mul_f32 v[202:203], v[48:49], v[182:183] op_sel_hi:[1,0]
	v_pk_mul_f32 v[204:205], v[50:51], v[182:183] op_sel_hi:[1,0]
	v_pk_add_f32 v[190:191], v[190:191], v[188:189]
	v_pk_add_f32 v[192:193], v[192:193], v[188:189]
	v_pk_add_f32 v[194:195], v[194:195], v[188:189]
	v_pk_add_f32 v[196:197], v[196:197], v[188:189]
	v_rcp_f32_e32 v190, v190
	v_rcp_f32_e32 v191, v191
	v_rcp_f32_e32 v192, v192
	v_rcp_f32_e32 v193, v193
	v_rcp_f32_e32 v194, v194
	v_rcp_f32_e32 v195, v195
	v_rcp_f32_e32 v196, v196
	v_rcp_f32_e32 v197, v197
	v_pk_mul_f32 v[198:199], v[198:199], v[190:191]
	v_pk_mul_f32 v[200:201], v[200:201], v[192:193]
	v_pk_mul_f32 v[202:203], v[202:203], v[194:195]
	v_pk_mul_f32 v[204:205], v[204:205], v[196:197]
	v_cvt_pk_bf16_f32 v134, v198, v199
	v_cvt_pk_bf16_f32 v135, v200, v201
	v_cvt_pk_bf16_f32 v136, v202, v203
	v_cvt_pk_bf16_f32 v137, v204, v205
; __device__ __forceinline__ float sigm_f(float v) { return __builtin_amdgcn_rcpf(1.0f + __builtin_amdgcn_exp2f(-1.44269504f * v)); }
; __device__ __forceinline__ float silu_f(float v) { return v * sigm_f(v); }
;     __device__ __forceinline__ void operator()(const f32x4 (&acc)[2][2][4][2], const Unit& u, int wr, int wc, int fr, int fq) const {
;     ...
; #pragma unroll
;                 for (int ai = 0; ai < 2; ++ai)
; #pragma unroll
;                     for (int m = 0; m < 4; ++m) { const int row = row0 + ai * HALF + m * 16; const float rsv = __builtin_amdgcn_rsqf(rs[row] * (1.0f / 1024.0f) + 1e-6f);
;                         bf16_t* rowp = O + (size_t)row * ldc + u.pn * BM + cw;
; #pragma unroll
;                         for (int bj = 0; bj < 2; ++bj) { f32x4 v0 = acc[ai][bj][m][0] * rsv, v1 = acc[ai][bj][m][1] * rsv;
;                             if (sub == 1) {
; #pragma unroll
;                                 for (int e = 0; e < 4; ++e) { v0[e] = silu_f(v0[e]); v1[e] = silu_f(v1[e]); } }
;                             else if (sub == 3) {
; #pragma unroll
;                                 for (int e = 0; e < 4; ++e) { v0[e] = sigm_f(v0[e]); v1[e] = sigm_f(v1[e]); } }
;                             store8(rowp + bj * HALF, v0, v1); } }
	flat_store_dwordx4 v[172:173], v[134:137]
	v_pk_mul_f32 v[190:191], v[28:29], v[184:185] op_sel_hi:[1,0]
	v_pk_mul_f32 v[192:193], v[30:31], v[184:185] op_sel_hi:[1,0]
	v_pk_mul_f32 v[194:195], v[24:25], v[184:185] op_sel_hi:[1,0]
	v_pk_mul_f32 v[196:197], v[26:27], v[184:185] op_sel_hi:[1,0]
	v_exp_f32_e32 v190, v190
	v_exp_f32_e32 v191, v191
	v_exp_f32_e32 v192, v192
	v_exp_f32_e32 v193, v193
	v_exp_f32_e32 v194, v194
	v_exp_f32_e32 v195, v195
	v_exp_f32_e32 v196, v196
	v_exp_f32_e32 v197, v197
	v_pk_mul_f32 v[198:199], v[28:29], v[182:183] op_sel_hi:[1,0]
	v_pk_mul_f32 v[200:201], v[30:31], v[182:183] op_sel_hi:[1,0]
	v_pk_mul_f32 v[202:203], v[24:25], v[182:183] op_sel_hi:[1,0]
	v_pk_mul_f32 v[204:205], v[26:27], v[182:183] op_sel_hi:[1,0]
	v_pk_add_f32 v[190:191], v[190:191], v[188:189]
	v_pk_add_f32 v[192:193], v[192:193], v[188:189]
	v_pk_add_f32 v[194:195], v[194:195], v[188:189]
	v_pk_add_f32 v[196:197], v[196:197], v[188:189]
	v_rcp_f32_e32 v190, v190
	v_rcp_f32_e32 v191, v191
	v_rcp_f32_e32 v192, v192
	v_rcp_f32_e32 v193, v193
	v_rcp_f32_e32 v194, v194
	v_rcp_f32_e32 v195, v195
	v_rcp_f32_e32 v196, v196
	v_rcp_f32_e32 v197, v197
	v_pk_mul_f32 v[198:199], v[198:199], v[190:191]
	v_pk_mul_f32 v[200:201], v[200:201], v[192:193]
	v_pk_mul_f32 v[202:203], v[202:203], v[194:195]
	v_pk_mul_f32 v[204:205], v[204:205], v[196:197]
	v_cvt_pk_bf16_f32 v212, v198, v199
	v_cvt_pk_bf16_f32 v213, v200, v201
	v_cvt_pk_bf16_f32 v214, v202, v203
	v_cvt_pk_bf16_f32 v215, v204, v205
	flat_store_dwordx4 v[172:173], v[212:215] offset:256
	v_fmamk_f32 v206, v253, 0x3a800000, v237
	v_rsq_f32_e32 v182, v206
	v_add_u32_e32 v207, 0xa0, v164
	v_mad_i64_i32 v[172:173], s[98:99], s82, v207, 0
	v_lshl_add_u64 v[172:173], v[172:173], 1, s[84:85]
	v_lshl_add_u64 v[172:173], s[62:63], 1, v[172:173]
	v_lshl_add_u64 v[172:173], v[148:149], 1, v[172:173]
	v_mul_f32_e32 v184, 0xbfb8aa3b, v182
	v_pk_mul_f32 v[190:191], v[36:37], v[184:185] op_sel_hi:[1,0]
	v_pk_mul_f32 v[192:193], v[38:39], v[184:185] op_sel_hi:[1,0]
	v_pk_mul_f32 v[194:195], v[32:33], v[184:185] op_sel_hi:[1,0]
	v_pk_mul_f32 v[196:197], v[34:35], v[184:185] op_sel_hi:[1,0]
	v_exp_f32_e32 v190, v190
	v_exp_f32_e32 v191, v191
	v_exp_f32_e32 v192, v192
	v_exp_f32_e32 v193, v193
	v_exp_f32_e32 v194, v194
	v_exp_f32_e32 v195, v195
	v_exp_f32_e32 v196, v196
	v_exp_f32_e32 v197, v197
	v_pk_mul_f32 v[198:199], v[36:37], v[182:183] op_sel_hi:[1,0]
	v_pk_mul_f32 v[200:201], v[38:39], v[182:183] op_sel_hi:[1,0]
	v_pk_mul_f32 v[202:203], v[32:33], v[182:183] op_sel_hi:[1,0]
	v_pk_mul_f32 v[204:205], v[34:35], v[182:183] op_sel_hi:[1,0]
	v_pk_add_f32 v[190:191], v[190:191], v[188:189]
	v_pk_add_f32 v[192:193], v[192:193], v[188:189]
	v_pk_add_f32 v[194:195], v[194:195], v[188:189]
	v_pk_add_f32 v[196:197], v[196:197], v[188:189]
	v_rcp_f32_e32 v190, v190
	v_rcp_f32_e32 v191, v191
	v_rcp_f32_e32 v192, v192
	v_rcp_f32_e32 v193, v193
	v_rcp_f32_e32 v194, v194
	v_rcp_f32_e32 v195, v195
	v_rcp_f32_e32 v196, v196
	v_rcp_f32_e32 v197, v197
	v_pk_mul_f32 v[198:199], v[198:199], v[190:191]
	v_pk_mul_f32 v[200:201], v[200:201], v[192:193]
	v_pk_mul_f32 v[202:203], v[202:203], v[194:195]
	v_pk_mul_f32 v[204:205], v[204:205], v[196:197]
	v_cvt_pk_bf16_f32 v134, v198, v199
	v_cvt_pk_bf16_f32 v135, v200, v201
	v_cvt_pk_bf16_f32 v136, v202, v203
	v_cvt_pk_bf16_f32 v137, v204, v205
	flat_store_dwordx4 v[172:173], v[134:137]
	v_pk_mul_f32 v[190:191], v[12:13], v[184:185] op_sel_hi:[1,0]
	v_pk_mul_f32 v[192:193], v[14:15], v[184:185] op_sel_hi:[1,0]
	v_pk_mul_f32 v[194:195], v[8:9], v[184:185] op_sel_hi:[1,0]
	v_pk_mul_f32 v[196:197], v[10:11], v[184:185] op_sel_hi:[1,0]
	v_exp_f32_e32 v190, v190
	v_exp_f32_e32 v191, v191
	v_exp_f32_e32 v192, v192
	v_exp_f32_e32 v193, v193
	v_exp_f32_e32 v194, v194
	v_exp_f32_e32 v195, v195
	v_exp_f32_e32 v196, v196
	v_exp_f32_e32 v197, v197
	v_pk_mul_f32 v[198:199], v[12:13], v[182:183] op_sel_hi:[1,0]
	v_pk_mul_f32 v[200:201], v[14:15], v[182:183] op_sel_hi:[1,0]
	v_pk_mul_f32 v[202:203], v[8:9], v[182:183] op_sel_hi:[1,0]
	v_pk_mul_f32 v[204:205], v[10:11], v[182:183] op_sel_hi:[1,0]
	v_pk_add_f32 v[190:191], v[190:191], v[188:189]
	v_pk_add_f32 v[192:193], v[192:193], v[188:189]
	v_pk_add_f32 v[194:195], v[194:195], v[188:189]
	v_pk_add_f32 v[196:197], v[196:197], v[188:189]
	v_rcp_f32_e32 v190, v190
	v_rcp_f32_e32 v191, v191
	v_rcp_f32_e32 v192, v192
	v_rcp_f32_e32 v193, v193
	v_rcp_f32_e32 v194, v194
	v_rcp_f32_e32 v195, v195
	v_rcp_f32_e32 v196, v196
	v_rcp_f32_e32 v197, v197
	v_pk_mul_f32 v[198:199], v[198:199], v[190:191]
	v_pk_mul_f32 v[200:201], v[200:201], v[192:193]
	v_pk_mul_f32 v[202:203], v[202:203], v[194:195]
	v_pk_mul_f32 v[204:205], v[204:205], v[196:197]
	v_cvt_pk_bf16_f32 v212, v198, v199
	v_cvt_pk_bf16_f32 v213, v200, v201
	v_cvt_pk_bf16_f32 v214, v202, v203
	v_cvt_pk_bf16_f32 v215, v204, v205
	flat_store_dwordx4 v[172:173], v[212:215] offset:256
	v_fmamk_f32 v206, v255, 0x3a800000, v237
	v_rsq_f32_e32 v182, v206
	v_add_u32_e32 v207, 0xb0, v164
	v_mad_i64_i32 v[172:173], s[98:99], s82, v207, 0
	v_lshl_add_u64 v[172:173], v[172:173], 1, s[84:85]
	v_lshl_add_u64 v[172:173], s[62:63], 1, v[172:173]
	v_lshl_add_u64 v[172:173], v[148:149], 1, v[172:173]
	v_mul_f32_e32 v184, 0xbfb8aa3b, v182
	v_pk_mul_f32 v[190:191], v[20:21], v[184:185] op_sel_hi:[1,0]
	v_pk_mul_f32 v[192:193], v[22:23], v[184:185] op_sel_hi:[1,0]
	v_pk_mul_f32 v[194:195], v[16:17], v[184:185] op_sel_hi:[1,0]
	v_pk_mul_f32 v[196:197], v[18:19], v[184:185] op_sel_hi:[1,0]
	v_exp_f32_e32 v190, v190
	v_exp_f32_e32 v191, v191
	v_exp_f32_e32 v192, v192
	v_exp_f32_e32 v193, v193
	v_exp_f32_e32 v194, v194
; __device__ __forceinline__ float sigm_f(float v) { return __builtin_amdgcn_rcpf(1.0f + __builtin_amdgcn_exp2f(-1.44269504f * v)); }
; __device__ __forceinline__ float silu_f(float v) { return v * sigm_f(v); }
;     __device__ __forceinline__ void operator()(const f32x4 (&acc)[2][2][4][2], const Unit& u, int wr, int wc, int fr, int fq) const {
;     ...
; #pragma unroll
;                 for (int ai = 0; ai < 2; ++ai)
; #pragma unroll
;                     for (int m = 0; m < 4; ++m) { const int row = row0 + ai * HALF + m * 16; const float rsv = __builtin_amdgcn_rsqf(rs[row] * (1.0f / 1024.0f) + 1e-6f);
;                         bf16_t* rowp = O + (size_t)row * ldc + u.pn * BM + cw;
; #pragma unroll
;                         for (int bj = 0; bj < 2; ++bj) { f32x4 v0 = acc[ai][bj][m][0] * rsv, v1 = acc[ai][bj][m][1] * rsv;
;                             if (sub == 1) {
; #pragma unroll
;                                 for (int e = 0; e < 4; ++e) { v0[e] = silu_f(v0[e]); v1[e] = silu_f(v1[e]); } }
;                             else if (sub == 3) {
; #pragma unroll
;                                 for (int e = 0; e < 4; ++e) { v0[e] = sigm_f(v0[e]); v1[e] = sigm_f(v1[e]); } }
;                             store8(rowp + bj * HALF, v0, v1); } }
	v_exp_f32_e32 v195, v195
	v_exp_f32_e32 v196, v196
	v_exp_f32_e32 v197, v197
	v_pk_mul_f32 v[198:199], v[20:21], v[182:183] op_sel_hi:[1,0]
	v_pk_mul_f32 v[200:201], v[22:23], v[182:183] op_sel_hi:[1,0]
	v_pk_mul_f32 v[202:203], v[16:17], v[182:183] op_sel_hi:[1,0]
	v_pk_mul_f32 v[204:205], v[18:19], v[182:183] op_sel_hi:[1,0]
	v_pk_add_f32 v[190:191], v[190:191], v[188:189]
	v_pk_add_f32 v[192:193], v[192:193], v[188:189]
	v_pk_add_f32 v[194:195], v[194:195], v[188:189]
	v_pk_add_f32 v[196:197], v[196:197], v[188:189]
	v_rcp_f32_e32 v190, v190
	v_rcp_f32_e32 v191, v191
	v_rcp_f32_e32 v192, v192
	v_rcp_f32_e32 v193, v193
	v_rcp_f32_e32 v194, v194
	v_rcp_f32_e32 v195, v195
	v_rcp_f32_e32 v196, v196
	v_rcp_f32_e32 v197, v197
	v_pk_mul_f32 v[198:199], v[198:199], v[190:191]
	v_pk_mul_f32 v[200:201], v[200:201], v[192:193]
	v_pk_mul_f32 v[202:203], v[202:203], v[194:195]
	v_pk_mul_f32 v[204:205], v[204:205], v[196:197]
	v_cvt_pk_bf16_f32 v134, v198, v199
	v_cvt_pk_bf16_f32 v135, v200, v201
	v_cvt_pk_bf16_f32 v136, v202, v203
	v_cvt_pk_bf16_f32 v137, v204, v205
	flat_store_dwordx4 v[172:173], v[134:137]
	v_pk_mul_f32 v[190:191], v[4:5], v[184:185] op_sel_hi:[1,0]
	v_pk_mul_f32 v[192:193], v[6:7], v[184:185] op_sel_hi:[1,0]
	v_pk_mul_f32 v[194:195], v[0:1], v[184:185] op_sel_hi:[1,0]
	v_pk_mul_f32 v[196:197], v[2:3], v[184:185] op_sel_hi:[1,0]
	v_exp_f32_e32 v190, v190
	v_exp_f32_e32 v191, v191
	v_exp_f32_e32 v192, v192
	v_exp_f32_e32 v193, v193
	v_exp_f32_e32 v194, v194
	v_exp_f32_e32 v195, v195
	v_exp_f32_e32 v196, v196
	v_exp_f32_e32 v197, v197
	v_pk_mul_f32 v[198:199], v[4:5], v[182:183] op_sel_hi:[1,0]
	v_pk_mul_f32 v[200:201], v[6:7], v[182:183] op_sel_hi:[1,0]
	v_pk_mul_f32 v[202:203], v[0:1], v[182:183] op_sel_hi:[1,0]
	v_pk_mul_f32 v[204:205], v[2:3], v[182:183] op_sel_hi:[1,0]
	v_pk_add_f32 v[190:191], v[190:191], v[188:189]
	v_pk_add_f32 v[192:193], v[192:193], v[188:189]
	v_pk_add_f32 v[194:195], v[194:195], v[188:189]
	v_pk_add_f32 v[196:197], v[196:197], v[188:189]
	v_rcp_f32_e32 v190, v190
	v_rcp_f32_e32 v191, v191
	v_rcp_f32_e32 v192, v192
	v_rcp_f32_e32 v193, v193
	v_rcp_f32_e32 v194, v194
	v_rcp_f32_e32 v195, v195
	v_rcp_f32_e32 v196, v196
	v_rcp_f32_e32 v197, v197
	v_pk_mul_f32 v[198:199], v[198:199], v[190:191]
	v_pk_mul_f32 v[200:201], v[200:201], v[192:193]
	v_pk_mul_f32 v[202:203], v[202:203], v[194:195]
	v_pk_mul_f32 v[204:205], v[204:205], v[196:197]
	v_cvt_pk_bf16_f32 v212, v198, v199
	v_cvt_pk_bf16_f32 v213, v200, v201
	v_cvt_pk_bf16_f32 v214, v202, v203
	v_cvt_pk_bf16_f32 v215, v204, v205
	flat_store_dwordx4 v[172:173], v[212:215] offset:256
	s_branch .Lmix_done
.Lmix_plain:
	v_mov_b32_e32 v182, v130
	v_mad_i64_i32 v[172:173], s[98:99], s82, v164, 0
	v_lshl_add_u64 v[172:173], v[172:173], 1, s[84:85]
	v_lshl_add_u64 v[172:173], s[62:63], 1, v[172:173]
	v_lshl_add_u64 v[172:173], v[148:149], 1, v[172:173]
	v_pk_mul_f32 v[198:199], v[124:125], v[182:183] op_sel_hi:[1,0]
	v_pk_mul_f32 v[200:201], v[126:127], v[182:183] op_sel_hi:[1,0]
	v_pk_mul_f32 v[202:203], v[120:121], v[182:183] op_sel_hi:[1,0]
	v_pk_mul_f32 v[204:205], v[122:123], v[182:183] op_sel_hi:[1,0]
	v_cvt_pk_bf16_f32 v134, v198, v199
	v_cvt_pk_bf16_f32 v135, v200, v201
	v_cvt_pk_bf16_f32 v136, v202, v203
	v_cvt_pk_bf16_f32 v137, v204, v205
	flat_store_dwordx4 v[172:173], v[134:137]
	v_pk_mul_f32 v[198:199], v[108:109], v[182:183] op_sel_hi:[1,0]
	v_pk_mul_f32 v[200:201], v[110:111], v[182:183] op_sel_hi:[1,0]
	v_pk_mul_f32 v[202:203], v[104:105], v[182:183] op_sel_hi:[1,0]
	v_pk_mul_f32 v[204:205], v[106:107], v[182:183] op_sel_hi:[1,0]
	v_cvt_pk_bf16_f32 v212, v198, v199
	v_cvt_pk_bf16_f32 v213, v200, v201
	v_cvt_pk_bf16_f32 v214, v202, v203
	v_cvt_pk_bf16_f32 v215, v204, v205
	flat_store_dwordx4 v[172:173], v[212:215] offset:256
	v_fmamk_f32 v206, v247, 0x3a800000, v237
	v_rsq_f32_e32 v182, v206
	v_add_u32_e32 v207, 0x10, v164
	v_mad_i64_i32 v[172:173], s[98:99], s82, v207, 0
	v_lshl_add_u64 v[172:173], v[172:173], 1, s[84:85]
	v_lshl_add_u64 v[172:173], s[62:63], 1, v[172:173]
	v_lshl_add_u64 v[172:173], v[148:149], 1, v[172:173]
	v_pk_mul_f32 v[198:199], v[116:117], v[182:183] op_sel_hi:[1,0]
	v_pk_mul_f32 v[200:201], v[118:119], v[182:183] op_sel_hi:[1,0]
	v_pk_mul_f32 v[202:203], v[112:113], v[182:183] op_sel_hi:[1,0]
	v_pk_mul_f32 v[204:205], v[114:115], v[182:183] op_sel_hi:[1,0]
	v_cvt_pk_bf16_f32 v134, v198, v199
	v_cvt_pk_bf16_f32 v135, v200, v201
	v_cvt_pk_bf16_f32 v136, v202, v203
	v_cvt_pk_bf16_f32 v137, v204, v205
	flat_store_dwordx4 v[172:173], v[134:137]
	v_pk_mul_f32 v[198:199], v[92:93], v[182:183] op_sel_hi:[1,0]
	v_pk_mul_f32 v[200:201], v[94:95], v[182:183] op_sel_hi:[1,0]
	v_pk_mul_f32 v[202:203], v[88:89], v[182:183] op_sel_hi:[1,0]
	v_pk_mul_f32 v[204:205], v[90:91], v[182:183] op_sel_hi:[1,0]
	v_cvt_pk_bf16_f32 v212, v198, v199
	v_cvt_pk_bf16_f32 v213, v200, v201
	v_cvt_pk_bf16_f32 v214, v202, v203
	v_cvt_pk_bf16_f32 v215, v204, v205
	flat_store_dwordx4 v[172:173], v[212:215] offset:256
	v_fmamk_f32 v206, v248, 0x3a800000, v237
	v_rsq_f32_e32 v182, v206
	v_add_u32_e32 v207, 0x20, v164
	v_mad_i64_i32 v[172:173], s[98:99], s82, v207, 0
	v_lshl_add_u64 v[172:173], v[172:173], 1, s[84:85]
	v_lshl_add_u64 v[172:173], s[62:63], 1, v[172:173]
	v_lshl_add_u64 v[172:173], v[148:149], 1, v[172:173]
	v_pk_mul_f32 v[198:199], v[100:101], v[182:183] op_sel_hi:[1,0]
	v_pk_mul_f32 v[200:201], v[102:103], v[182:183] op_sel_hi:[1,0]
	v_pk_mul_f32 v[202:203], v[96:97], v[182:183] op_sel_hi:[1,0]
	v_pk_mul_f32 v[204:205], v[98:99], v[182:183] op_sel_hi:[1,0]
	v_cvt_pk_bf16_f32 v134, v198, v199
	v_cvt_pk_bf16_f32 v135, v200, v201
; __device__ __forceinline__ float sigm_f(float v) { return __builtin_amdgcn_rcpf(1.0f + __builtin_amdgcn_exp2f(-1.44269504f * v)); }
; __device__ __forceinline__ float silu_f(float v) { return v * sigm_f(v); }
;     __device__ __forceinline__ void operator()(const f32x4 (&acc)[2][2][4][2], const Unit& u, int wr, int wc, int fr, int fq) const {
;     ...
; #pragma unroll
;                 for (int ai = 0; ai < 2; ++ai)
; #pragma unroll
;                     for (int m = 0; m < 4; ++m) { const int row = row0 + ai * HALF + m * 16; const float rsv = __builtin_amdgcn_rsqf(rs[row] * (1.0f / 1024.0f) + 1e-6f);
;                         bf16_t* rowp = O + (size_t)row * ldc + u.pn * BM + cw;
; #pragma unroll
;                         for (int bj = 0; bj < 2; ++bj) { f32x4 v0 = acc[ai][bj][m][0] * rsv, v1 = acc[ai][bj][m][1] * rsv;
;                             if (sub == 1) {
; #pragma unroll
;                                 for (int e = 0; e < 4; ++e) { v0[e] = silu_f(v0[e]); v1[e] = silu_f(v1[e]); } }
;                             else if (sub == 3) {
; #pragma unroll
;                                 for (int e = 0; e < 4; ++e) { v0[e] = sigm_f(v0[e]); v1[e] = sigm_f(v1[e]); } }
;                             store8(rowp + bj * HALF, v0, v1); } }
	v_cvt_pk_bf16_f32 v136, v202, v203
	v_cvt_pk_bf16_f32 v137, v204, v205
	flat_store_dwordx4 v[172:173], v[134:137]
	v_pk_mul_f32 v[198:199], v[76:77], v[182:183] op_sel_hi:[1,0]
	v_pk_mul_f32 v[200:201], v[78:79], v[182:183] op_sel_hi:[1,0]
	v_pk_mul_f32 v[202:203], v[72:73], v[182:183] op_sel_hi:[1,0]
	v_pk_mul_f32 v[204:205], v[74:75], v[182:183] op_sel_hi:[1,0]
	v_cvt_pk_bf16_f32 v212, v198, v199
	v_cvt_pk_bf16_f32 v213, v200, v201
	v_cvt_pk_bf16_f32 v214, v202, v203
	v_cvt_pk_bf16_f32 v215, v204, v205
	flat_store_dwordx4 v[172:173], v[212:215] offset:256
	v_fmamk_f32 v206, v249, 0x3a800000, v237
	v_rsq_f32_e32 v182, v206
	v_add_u32_e32 v207, 0x30, v164
	v_mad_i64_i32 v[172:173], s[98:99], s82, v207, 0
	v_lshl_add_u64 v[172:173], v[172:173], 1, s[84:85]
	v_lshl_add_u64 v[172:173], s[62:63], 1, v[172:173]
	v_lshl_add_u64 v[172:173], v[148:149], 1, v[172:173]
	v_pk_mul_f32 v[198:199], v[84:85], v[182:183] op_sel_hi:[1,0]
	v_pk_mul_f32 v[200:201], v[86:87], v[182:183] op_sel_hi:[1,0]
	v_pk_mul_f32 v[202:203], v[80:81], v[182:183] op_sel_hi:[1,0]
	v_pk_mul_f32 v[204:205], v[82:83], v[182:183] op_sel_hi:[1,0]
	v_cvt_pk_bf16_f32 v134, v198, v199
	v_cvt_pk_bf16_f32 v135, v200, v201
	v_cvt_pk_bf16_f32 v136, v202, v203
	v_cvt_pk_bf16_f32 v137, v204, v205
	flat_store_dwordx4 v[172:173], v[134:137]
	v_pk_mul_f32 v[198:199], v[68:69], v[182:183] op_sel_hi:[1,0]
	v_pk_mul_f32 v[200:201], v[70:71], v[182:183] op_sel_hi:[1,0]
	v_pk_mul_f32 v[202:203], v[64:65], v[182:183] op_sel_hi:[1,0]
	v_pk_mul_f32 v[204:205], v[66:67], v[182:183] op_sel_hi:[1,0]
	v_cvt_pk_bf16_f32 v212, v198, v199
	v_cvt_pk_bf16_f32 v213, v200, v201
	v_cvt_pk_bf16_f32 v214, v202, v203
	v_cvt_pk_bf16_f32 v215, v204, v205
	flat_store_dwordx4 v[172:173], v[212:215] offset:256
	v_fmamk_f32 v206, v250, 0x3a800000, v237
	v_rsq_f32_e32 v182, v206
	v_add_u32_e32 v207, 0x80, v164
	v_mad_i64_i32 v[172:173], s[98:99], s82, v207, 0
	v_lshl_add_u64 v[172:173], v[172:173], 1, s[84:85]
	v_lshl_add_u64 v[172:173], s[62:63], 1, v[172:173]
	v_lshl_add_u64 v[172:173], v[148:149], 1, v[172:173]
	v_pk_mul_f32 v[198:199], v[60:61], v[182:183] op_sel_hi:[1,0]
	v_pk_mul_f32 v[200:201], v[62:63], v[182:183] op_sel_hi:[1,0]
	v_pk_mul_f32 v[202:203], v[56:57], v[182:183] op_sel_hi:[1,0]
	v_pk_mul_f32 v[204:205], v[58:59], v[182:183] op_sel_hi:[1,0]
	v_cvt_pk_bf16_f32 v134, v198, v199
	v_cvt_pk_bf16_f32 v135, v200, v201
	v_cvt_pk_bf16_f32 v136, v202, v203
	v_cvt_pk_bf16_f32 v137, v204, v205
	flat_store_dwordx4 v[172:173], v[134:137]
	v_pk_mul_f32 v[198:199], v[44:45], v[182:183] op_sel_hi:[1,0]
	v_pk_mul_f32 v[200:201], v[46:47], v[182:183] op_sel_hi:[1,0]
	v_pk_mul_f32 v[202:203], v[40:41], v[182:183] op_sel_hi:[1,0]
	v_pk_mul_f32 v[204:205], v[42:43], v[182:183] op_sel_hi:[1,0]
	v_cvt_pk_bf16_f32 v212, v198, v199
	v_cvt_pk_bf16_f32 v213, v200, v201
	v_cvt_pk_bf16_f32 v214, v202, v203
	v_cvt_pk_bf16_f32 v215, v204, v205
	flat_store_dwordx4 v[172:173], v[212:215] offset:256
	v_fmamk_f32 v206, v252, 0x3a800000, v237
	v_rsq_f32_e32 v182, v206
	v_add_u32_e32 v207, 0x90, v164
	v_mad_i64_i32 v[172:173], s[98:99], s82, v207, 0
	v_lshl_add_u64 v[172:173], v[172:173], 1, s[84:85]
	v_lshl_add_u64 v[172:173], s[62:63], 1, v[172:173]
	v_lshl_add_u64 v[172:173], v[148:149], 1, v[172:173]
	v_pk_mul_f32 v[198:199], v[52:53], v[182:183] op_sel_hi:[1,0]
	v_pk_mul_f32 v[200:201], v[54:55], v[182:183] op_sel_hi:[1,0]
	v_pk_mul_f32 v[202:203], v[48:49], v[182:183] op_sel_hi:[1,0]
	v_pk_mul_f32 v[204:205], v[50:51], v[182:183] op_sel_hi:[1,0]
	v_cvt_pk_bf16_f32 v134, v198, v199
	v_cvt_pk_bf16_f32 v135, v200, v201
	v_cvt_pk_bf16_f32 v136, v202, v203
	v_cvt_pk_bf16_f32 v137, v204, v205
	flat_store_dwordx4 v[172:173], v[134:137]
	v_pk_mul_f32 v[198:199], v[28:29], v[182:183] op_sel_hi:[1,0]
	v_pk_mul_f32 v[200:201], v[30:31], v[182:183] op_sel_hi:[1,0]
	v_pk_mul_f32 v[202:203], v[24:25], v[182:183] op_sel_hi:[1,0]
	v_pk_mul_f32 v[204:205], v[26:27], v[182:183] op_sel_hi:[1,0]
	v_cvt_pk_bf16_f32 v212, v198, v199
	v_cvt_pk_bf16_f32 v213, v200, v201
	v_cvt_pk_bf16_f32 v214, v202, v203
	v_cvt_pk_bf16_f32 v215, v204, v205
	flat_store_dwordx4 v[172:173], v[212:215] offset:256
	v_fmamk_f32 v206, v253, 0x3a800000, v237
	v_rsq_f32_e32 v182, v206
	v_add_u32_e32 v207, 0xa0, v164
	v_mad_i64_i32 v[172:173], s[98:99], s82, v207, 0
	v_lshl_add_u64 v[172:173], v[172:173], 1, s[84:85]
	v_lshl_add_u64 v[172:173], s[62:63], 1, v[172:173]
	v_lshl_add_u64 v[172:173], v[148:149], 1, v[172:173]
	v_pk_mul_f32 v[198:199], v[36:37], v[182:183] op_sel_hi:[1,0]
	v_pk_mul_f32 v[200:201], v[38:39], v[182:183] op_sel_hi:[1,0]
	v_pk_mul_f32 v[202:203], v[32:33], v[182:183] op_sel_hi:[1,0]
	v_pk_mul_f32 v[204:205], v[34:35], v[182:183] op_sel_hi:[1,0]
	v_cvt_pk_bf16_f32 v134, v198, v199
	v_cvt_pk_bf16_f32 v135, v200, v201
	v_cvt_pk_bf16_f32 v136, v202, v203
	v_cvt_pk_bf16_f32 v137, v204, v205
	flat_store_dwordx4 v[172:173], v[134:137]
	v_pk_mul_f32 v[198:199], v[12:13], v[182:183] op_sel_hi:[1,0]
	v_pk_mul_f32 v[200:201], v[14:15], v[182:183] op_sel_hi:[1,0]
	v_pk_mul_f32 v[202:203], v[8:9], v[182:183] op_sel_hi:[1,0]
	v_pk_mul_f32 v[204:205], v[10:11], v[182:183] op_sel_hi:[1,0]
	v_cvt_pk_bf16_f32 v212, v198, v199
	v_cvt_pk_bf16_f32 v213, v200, v201
	v_cvt_pk_bf16_f32 v214, v202, v203
	v_cvt_pk_bf16_f32 v215, v204, v205
	flat_store_dwordx4 v[172:173], v[212:215] offset:256
	v_fmamk_f32 v206, v255, 0x3a800000, v237
	v_rsq_f32_e32 v182, v206
	v_add_u32_e32 v207, 0xb0, v164
	v_mad_i64_i32 v[172:173], s[98:99], s82, v207, 0
	v_lshl_add_u64 v[172:173], v[172:173], 1, s[84:85]
	v_lshl_add_u64 v[172:173], s[62:63], 1, v[172:173]
	v_lshl_add_u64 v[172:173], v[148:149], 1, v[172:173]
	v_pk_mul_f32 v[198:199], v[20:21], v[182:183] op_sel_hi:[1,0]
	v_pk_mul_f32 v[200:201], v[22:23], v[182:183] op_sel_hi:[1,0]
	v_pk_mul_f32 v[202:203], v[16:17], v[182:183] op_sel_hi:[1,0]
	v_pk_mul_f32 v[204:205], v[18:19], v[182:183] op_sel_hi:[1,0]
	v_cvt_pk_bf16_f32 v134, v198, v199
	v_cvt_pk_bf16_f32 v135, v200, v201
	v_cvt_pk_bf16_f32 v136, v202, v203
	v_cvt_pk_bf16_f32 v137, v204, v205
	flat_store_dwordx4 v[172:173], v[134:137]
	v_pk_mul_f32 v[198:199], v[4:5], v[182:183] op_sel_hi:[1,0]
	v_pk_mul_f32 v[200:201], v[6:7], v[182:183] op_sel_hi:[1,0]
	v_pk_mul_f32 v[202:203], v[0:1], v[182:183] op_sel_hi:[1,0]
	v_pk_mul_f32 v[204:205], v[2:3], v[182:183] op_sel_hi:[1,0]
	v_cvt_pk_bf16_f32 v212, v198, v199
	v_cvt_pk_bf16_f32 v213, v200, v201
	v_cvt_pk_bf16_f32 v214, v202, v203
	v_cvt_pk_bf16_f32 v215, v204, v205
	flat_store_dwordx4 v[172:173], v[212:215] offset:256
;     __device__ __forceinline__ void operator()(const f32x4 (&acc)[2][2][4][2], const Unit& u, int wr, int wc, int fr, int fq) const {
;     ...
;                 const int i0 = 32 * (wc & 1) + 8 * fq;
; #pragma unroll
;                 for (int ai = 0; ai < 2; ++ai)
; #pragma unroll
;                     for (int m = 0; m < 4; ++m) { const int row = row0 + ai * HALF + m * 16; const float rsv = __builtin_amdgcn_rsqf(rs[row] * (1.0f / 1024.0f) + 1e-6f); const int pos = row & 2047;
;                         const f32x4 c0 = *(const f32x4*)(cs + pos * 64 + i0), c1 = *(const f32x4*)(cs + pos * 64 + i0 + 4);
;                         const f32x4 s0 = *(const f32x4*)(sn + pos * 64 + i0), s1 = *(const f32x4*)(sn + pos * 64 + i0 + 4);
;                         const f32x4 x1a = acc[ai][0][m][0] * rsv, x1b = acc[ai][0][m][1] * rsv, x2a = acc[ai][1][m][0] * rsv, x2b = acc[ai][1][m][1] * rsv;
;                         bf16_t* rowp = O + (size_t)row * ldc + u.pn * BM + cw;
;                         store8(rowp, x1a * c0 - x2a * s0, x1b * c1 - x2b * s1);
;                         store8(rowp + HALF, x1a * s0 + x2a * c0, x1b * s1 + x2b * c1); }
.Lmix_done:
	s_mov_b64 s[6:7], 0
.LBB0_585:
	s_and_b64 vcc, exec, s[6:7]
	s_cbranch_vccz .LBB0_587
	v_lshlrev_b32_e32 v131, 8, v164
	v_and_b32_e32 v176, 0x7cf00, v131
	v_lshl_add_u64 v[136:137], v[158:159], 0, v[176:177]
	flat_load_dwordx4 v[132:135], v[136:137]
	s_nop 0
	flat_load_dwordx4 v[136:139], v[136:137] offset:16
	v_lshl_add_u64 v[170:171], v[156:157], 0, v[176:177]
	flat_load_dwordx4 v[166:169], v[170:171]
	s_nop 0
	flat_load_dwordx4 v[170:173], v[170:171] offset:16
	s_ashr_i32 s7, s62, 31
	s_mov_b32 s6, s62
	v_pk_mul_f32 v[186:187], v[110:111], v[130:131] op_sel_hi:[1,0]
	v_pk_mul_f32 v[188:189], v[108:109], v[130:131] op_sel_hi:[1,0]
	v_pk_mul_f32 v[190:191], v[106:107], v[130:131] op_sel_hi:[1,0]
	v_pk_mul_f32 v[192:193], v[104:105], v[130:131] op_sel_hi:[1,0]
	v_mad_i64_i32 v[194:195], s[38:39], s82, v164, 0
	v_pk_mul_f32 v[174:175], v[126:127], v[130:131] op_sel_hi:[1,0]
	v_pk_mul_f32 v[178:179], v[124:125], v[130:131] op_sel_hi:[1,0]
	v_pk_mul_f32 v[182:183], v[122:123], v[130:131] op_sel_hi:[1,0]
	v_pk_mul_f32 v[184:185], v[120:121], v[130:131] op_sel_hi:[1,0]
	v_lshl_add_u64 v[194:195], v[194:195], 1, s[84:85]
	s_lshl_b64 s[6:7], s[6:7], 1
	v_lshlrev_b64 v[130:131], 1, v[148:149]
	v_lshl_add_u64 v[194:195], v[194:195], 0, s[6:7]
	v_lshl_add_u64 v[194:195], v[194:195], 0, v[130:131]
	s_waitcnt vmcnt(0) lgkmcnt(0)
	v_pk_mul_f32 v[196:197], v[186:187], v[134:135]
	v_pk_mul_f32 v[198:199], v[188:189], v[132:133]
	v_pk_mul_f32 v[200:201], v[190:191], v[138:139]
	v_pk_mul_f32 v[202:203], v[192:193], v[136:137]
	v_pk_mul_f32 v[134:135], v[174:175], v[134:135]
	v_pk_mul_f32 v[132:133], v[178:179], v[132:133]
	v_pk_mul_f32 v[138:139], v[182:183], v[138:139]
	v_pk_mul_f32 v[136:137], v[184:185], v[136:137]
	v_pk_fma_f32 v[174:175], v[174:175], v[168:169], v[196:197] neg_lo:[0,0,1] neg_hi:[0,0,1]
	v_pk_fma_f32 v[178:179], v[178:179], v[166:167], v[198:199] neg_lo:[0,0,1] neg_hi:[0,0,1]
	v_pk_fma_f32 v[182:183], v[182:183], v[172:173], v[200:201] neg_lo:[0,0,1] neg_hi:[0,0,1]
	v_pk_fma_f32 v[184:185], v[184:185], v[170:171], v[202:203] neg_lo:[0,0,1] neg_hi:[0,0,1]
	v_pk_fma_f32 v[168:169], v[186:187], v[168:169], v[134:135]
	v_pk_fma_f32 v[166:167], v[188:189], v[166:167], v[132:133]
	v_pk_fma_f32 v[172:173], v[190:191], v[172:173], v[138:139]
	v_pk_fma_f32 v[138:139], v[192:193], v[170:171], v[136:137]
	v_cvt_pk_bf16_f32 v132, v178, v179
	v_cvt_pk_bf16_f32 v133, v174, v175
	v_cvt_pk_bf16_f32 v134, v184, v185
	v_cvt_pk_bf16_f32 v135, v182, v183
	v_cvt_pk_bf16_f32 v136, v166, v167
	v_cvt_pk_bf16_f32 v137, v168, v169
	v_cvt_pk_bf16_f32 v138, v138, v139
	v_cvt_pk_bf16_f32 v139, v172, v173
	flat_store_dwordx4 v[194:195], v[132:135]
	flat_store_dwordx4 v[194:195], v[136:139] offset:256
	flat_load_dword v165, v[128:129] offset:64
	v_or_b32_e32 v174, 16, v164
	v_lshlrev_b32_e32 v132, 8, v174
	v_and_b32_e32 v176, 0x7df00, v132
	v_lshl_add_u64 v[136:137], v[158:159], 0, v[176:177]
	flat_load_dwordx4 v[132:135], v[136:137]
	s_nop 0
	flat_load_dwordx4 v[136:139], v[136:137] offset:16
	v_lshl_add_u64 v[170:171], v[156:157], 0, v[176:177]
	flat_load_dwordx4 v[166:169], v[170:171]
	s_nop 0
	flat_load_dwordx4 v[170:173], v[170:171] offset:16
	v_mad_i64_i32 v[174:175], s[38:39], s82, v174, 0
	v_lshl_add_u64 v[174:175], v[174:175], 1, s[84:85]
	v_lshl_add_u64 v[174:175], v[174:175], 0, s[6:7]
	v_lshl_add_u64 v[174:175], v[174:175], 0, v[130:131]
	s_waitcnt vmcnt(0) lgkmcnt(0)
	v_fmamk_f32 v165, v165, 0x3a800000, v237
	v_rsq_f32_e32 v176, v165
	s_nop 0
	v_pk_mul_f32 v[188:189], v[92:93], v[176:177] op_sel_hi:[1,0]
	v_pk_mul_f32 v[190:191], v[94:95], v[176:177] op_sel_hi:[1,0]
	v_pk_mul_f32 v[192:193], v[88:89], v[176:177] op_sel_hi:[1,0]
	v_pk_mul_f32 v[194:195], v[90:91], v[176:177] op_sel_hi:[1,0]
	v_pk_mul_f32 v[178:179], v[116:117], v[176:177] op_sel_hi:[1,0]
	v_pk_mul_f32 v[182:183], v[118:119], v[176:177] op_sel_hi:[1,0]
	v_pk_mul_f32 v[184:185], v[112:113], v[176:177] op_sel_hi:[1,0]
	v_pk_mul_f32 v[186:187], v[114:115], v[176:177] op_sel_hi:[1,0]
	v_pk_mul_f32 v[196:197], v[134:135], v[190:191]
	v_pk_mul_f32 v[198:199], v[132:133], v[188:189]
	v_pk_mul_f32 v[200:201], v[138:139], v[194:195]
	v_pk_mul_f32 v[202:203], v[136:137], v[192:193]
	v_pk_mul_f32 v[190:191], v[168:169], v[190:191]
	v_pk_mul_f32 v[188:189], v[166:167], v[188:189]
	v_pk_mul_f32 v[194:195], v[172:173], v[194:195]
	v_pk_mul_f32 v[192:193], v[170:171], v[192:193]
	v_pk_fma_f32 v[168:169], v[168:169], v[182:183], v[196:197] neg_lo:[0,0,1] neg_hi:[0,0,1]
	v_pk_fma_f32 v[166:167], v[166:167], v[178:179], v[198:199] neg_lo:[0,0,1] neg_hi:[0,0,1]
	v_pk_fma_f32 v[172:173], v[172:173], v[186:187], v[200:201] neg_lo:[0,0,1] neg_hi:[0,0,1]
	v_pk_fma_f32 v[170:171], v[170:171], v[184:185], v[202:203] neg_lo:[0,0,1] neg_hi:[0,0,1]
	v_pk_fma_f32 v[182:183], v[134:135], v[182:183], v[190:191]
	v_pk_fma_f32 v[178:179], v[132:133], v[178:179], v[188:189]
	v_pk_fma_f32 v[186:187], v[138:139], v[186:187], v[194:195]
	v_pk_fma_f32 v[138:139], v[136:137], v[184:185], v[192:193]
	v_cvt_pk_bf16_f32 v132, v166, v167
	v_cvt_pk_bf16_f32 v133, v168, v169
	v_cvt_pk_bf16_f32 v134, v170, v171
	v_cvt_pk_bf16_f32 v135, v172, v173
	v_cvt_pk_bf16_f32 v136, v178, v179
	v_cvt_pk_bf16_f32 v137, v182, v183
	v_cvt_pk_bf16_f32 v138, v138, v139
	v_cvt_pk_bf16_f32 v139, v186, v187
	flat_store_dwordx4 v[174:175], v[132:135]
	flat_store_dwordx4 v[174:175], v[136:139] offset:256
	flat_load_dword v165, v[128:129] offset:128
	v_or_b32_e32 v174, 32, v164
	v_lshlrev_b32_e32 v132, 8, v174
	v_and_b32_e32 v176, 0x7ef00, v132
	v_lshl_add_u64 v[136:137], v[158:159], 0, v[176:177]
	flat_load_dwordx4 v[132:135], v[136:137]
	s_nop 0
	flat_load_dwordx4 v[136:139], v[136:137] offset:16
	v_lshl_add_u64 v[170:171], v[156:157], 0, v[176:177]
	flat_load_dwordx4 v[166:169], v[170:171]
	s_nop 0
	flat_load_dwordx4 v[170:173], v[170:171] offset:16
	v_mad_i64_i32 v[174:175], s[38:39], s82, v174, 0
	v_lshl_add_u64 v[174:175], v[174:175], 1, s[84:85]
	v_lshl_add_u64 v[174:175], v[174:175], 0, s[6:7]
	v_lshl_add_u64 v[174:175], v[174:175], 0, v[130:131]
	s_waitcnt vmcnt(0) lgkmcnt(0)
;     __device__ __forceinline__ void operator()(const f32x4 (&acc)[2][2][4][2], const Unit& u, int wr, int wc, int fr, int fq) const {
;     ...
;                 const int i0 = 32 * (wc & 1) + 8 * fq;
; #pragma unroll
;                 for (int ai = 0; ai < 2; ++ai)
; #pragma unroll
;                     for (int m = 0; m < 4; ++m) { const int row = row0 + ai * HALF + m * 16; const float rsv = __builtin_amdgcn_rsqf(rs[row] * (1.0f / 1024.0f) + 1e-6f); const int pos = row & 2047;
;                         const f32x4 c0 = *(const f32x4*)(cs + pos * 64 + i0), c1 = *(const f32x4*)(cs + pos * 64 + i0 + 4);
;                         const f32x4 s0 = *(const f32x4*)(sn + pos * 64 + i0), s1 = *(const f32x4*)(sn + pos * 64 + i0 + 4);
;                         const f32x4 x1a = acc[ai][0][m][0] * rsv, x1b = acc[ai][0][m][1] * rsv, x2a = acc[ai][1][m][0] * rsv, x2b = acc[ai][1][m][1] * rsv;
;                         bf16_t* rowp = O + (size_t)row * ldc + u.pn * BM + cw;
;                         store8(rowp, x1a * c0 - x2a * s0, x1b * c1 - x2b * s1);
;                         store8(rowp + HALF, x1a * s0 + x2a * c0, x1b * s1 + x2b * c1); }
	v_fmamk_f32 v165, v165, 0x3a800000, v237
	v_rsq_f32_e32 v176, v165
	s_nop 0
	v_pk_mul_f32 v[188:189], v[76:77], v[176:177] op_sel_hi:[1,0]
	v_pk_mul_f32 v[190:191], v[78:79], v[176:177] op_sel_hi:[1,0]
	v_pk_mul_f32 v[192:193], v[72:73], v[176:177] op_sel_hi:[1,0]
	v_pk_mul_f32 v[194:195], v[74:75], v[176:177] op_sel_hi:[1,0]
	v_pk_mul_f32 v[178:179], v[100:101], v[176:177] op_sel_hi:[1,0]
	v_pk_mul_f32 v[182:183], v[102:103], v[176:177] op_sel_hi:[1,0]
	v_pk_mul_f32 v[184:185], v[96:97], v[176:177] op_sel_hi:[1,0]
	v_pk_mul_f32 v[186:187], v[98:99], v[176:177] op_sel_hi:[1,0]
	v_pk_mul_f32 v[196:197], v[134:135], v[190:191]
	v_pk_mul_f32 v[198:199], v[132:133], v[188:189]
	v_pk_mul_f32 v[200:201], v[138:139], v[194:195]
	v_pk_mul_f32 v[202:203], v[136:137], v[192:193]
	v_pk_mul_f32 v[190:191], v[168:169], v[190:191]
	v_pk_mul_f32 v[188:189], v[166:167], v[188:189]
	v_pk_mul_f32 v[194:195], v[172:173], v[194:195]
	v_pk_mul_f32 v[192:193], v[170:171], v[192:193]
	v_pk_fma_f32 v[168:169], v[168:169], v[182:183], v[196:197] neg_lo:[0,0,1] neg_hi:[0,0,1]
	v_pk_fma_f32 v[166:167], v[166:167], v[178:179], v[198:199] neg_lo:[0,0,1] neg_hi:[0,0,1]
	v_pk_fma_f32 v[172:173], v[172:173], v[186:187], v[200:201] neg_lo:[0,0,1] neg_hi:[0,0,1]
	v_pk_fma_f32 v[170:171], v[170:171], v[184:185], v[202:203] neg_lo:[0,0,1] neg_hi:[0,0,1]
	v_pk_fma_f32 v[182:183], v[134:135], v[182:183], v[190:191]
	v_pk_fma_f32 v[178:179], v[132:133], v[178:179], v[188:189]
	v_pk_fma_f32 v[186:187], v[138:139], v[186:187], v[194:195]
	v_pk_fma_f32 v[138:139], v[136:137], v[184:185], v[192:193]
	v_cvt_pk_bf16_f32 v132, v166, v167
	v_cvt_pk_bf16_f32 v133, v168, v169
	v_cvt_pk_bf16_f32 v134, v170, v171
	v_cvt_pk_bf16_f32 v135, v172, v173
	v_cvt_pk_bf16_f32 v136, v178, v179
	v_cvt_pk_bf16_f32 v137, v182, v183
	v_cvt_pk_bf16_f32 v138, v138, v139
	v_cvt_pk_bf16_f32 v139, v186, v187
	flat_store_dwordx4 v[174:175], v[132:135]
	flat_store_dwordx4 v[174:175], v[136:139] offset:256
	flat_load_dword v165, v[128:129] offset:192
	v_or_b32_e32 v174, 48, v164
	v_lshlrev_b32_e32 v132, 8, v174
	v_and_b32_e32 v176, 0x7ff00, v132
	v_lshl_add_u64 v[136:137], v[158:159], 0, v[176:177]
	flat_load_dwordx4 v[132:135], v[136:137]
	s_nop 0
	flat_load_dwordx4 v[136:139], v[136:137] offset:16
	v_lshl_add_u64 v[170:171], v[156:157], 0, v[176:177]
	flat_load_dwordx4 v[166:169], v[170:171]
	s_nop 0
	flat_load_dwordx4 v[170:173], v[170:171] offset:16
	v_mad_i64_i32 v[174:175], s[38:39], s82, v174, 0
	v_lshl_add_u64 v[174:175], v[174:175], 1, s[84:85]
	v_lshl_add_u64 v[174:175], v[174:175], 0, s[6:7]
	v_lshl_add_u64 v[174:175], v[174:175], 0, v[130:131]
	s_waitcnt vmcnt(0) lgkmcnt(0)
	v_fmamk_f32 v165, v165, 0x3a800000, v237
	v_rsq_f32_e32 v176, v165
	s_nop 0
	v_pk_mul_f32 v[188:189], v[68:69], v[176:177] op_sel_hi:[1,0]
	v_pk_mul_f32 v[190:191], v[70:71], v[176:177] op_sel_hi:[1,0]
	v_pk_mul_f32 v[192:193], v[64:65], v[176:177] op_sel_hi:[1,0]
	v_pk_mul_f32 v[194:195], v[66:67], v[176:177] op_sel_hi:[1,0]
	v_pk_mul_f32 v[178:179], v[84:85], v[176:177] op_sel_hi:[1,0]
	v_pk_mul_f32 v[182:183], v[86:87], v[176:177] op_sel_hi:[1,0]
	v_pk_mul_f32 v[184:185], v[80:81], v[176:177] op_sel_hi:[1,0]
	v_pk_mul_f32 v[186:187], v[82:83], v[176:177] op_sel_hi:[1,0]
	v_pk_mul_f32 v[196:197], v[134:135], v[190:191]
	v_pk_mul_f32 v[198:199], v[132:133], v[188:189]
	v_pk_mul_f32 v[200:201], v[138:139], v[194:195]
	v_pk_mul_f32 v[202:203], v[136:137], v[192:193]
	v_pk_mul_f32 v[190:191], v[168:169], v[190:191]
	v_pk_mul_f32 v[188:189], v[166:167], v[188:189]
	v_pk_mul_f32 v[194:195], v[172:173], v[194:195]
	v_pk_mul_f32 v[192:193], v[170:171], v[192:193]
	v_pk_fma_f32 v[168:169], v[168:169], v[182:183], v[196:197] neg_lo:[0,0,1] neg_hi:[0,0,1]
	v_pk_fma_f32 v[166:167], v[166:167], v[178:179], v[198:199] neg_lo:[0,0,1] neg_hi:[0,0,1]
	v_pk_fma_f32 v[172:173], v[172:173], v[186:187], v[200:201] neg_lo:[0,0,1] neg_hi:[0,0,1]
	v_pk_fma_f32 v[170:171], v[170:171], v[184:185], v[202:203] neg_lo:[0,0,1] neg_hi:[0,0,1]
	v_pk_fma_f32 v[182:183], v[134:135], v[182:183], v[190:191]
	v_pk_fma_f32 v[178:179], v[132:133], v[178:179], v[188:189]
	v_pk_fma_f32 v[186:187], v[138:139], v[186:187], v[194:195]
	v_pk_fma_f32 v[138:139], v[136:137], v[184:185], v[192:193]
	v_cvt_pk_bf16_f32 v132, v166, v167
	v_cvt_pk_bf16_f32 v133, v168, v169
	v_cvt_pk_bf16_f32 v134, v170, v171
	v_cvt_pk_bf16_f32 v135, v172, v173
	v_cvt_pk_bf16_f32 v136, v178, v179
	v_cvt_pk_bf16_f32 v137, v182, v183
	v_cvt_pk_bf16_f32 v138, v138, v139
	v_cvt_pk_bf16_f32 v139, v186, v187
	flat_store_dwordx4 v[174:175], v[132:135]
	flat_store_dwordx4 v[174:175], v[136:139] offset:256
	flat_load_dword v165, v[128:129] offset:512
	v_add_u32_e32 v174, 0x80, v164
	v_lshlrev_b32_e32 v132, 8, v174
	v_and_b32_e32 v176, 0x7cf00, v132
	v_lshl_add_u64 v[136:137], v[158:159], 0, v[176:177]
	flat_load_dwordx4 v[132:135], v[136:137]
	s_nop 0
	flat_load_dwordx4 v[136:139], v[136:137] offset:16
	v_lshl_add_u64 v[170:171], v[156:157], 0, v[176:177]
	flat_load_dwordx4 v[166:169], v[170:171]
	s_nop 0
	flat_load_dwordx4 v[170:173], v[170:171] offset:16
	v_mad_i64_i32 v[174:175], s[38:39], s82, v174, 0
	v_lshl_add_u64 v[174:175], v[174:175], 1, s[84:85]
	v_lshl_add_u64 v[174:175], v[174:175], 0, s[6:7]
	v_lshl_add_u64 v[174:175], v[174:175], 0, v[130:131]
	s_waitcnt vmcnt(0) lgkmcnt(0)
;     __device__ __forceinline__ void operator()(const f32x4 (&acc)[2][2][4][2], const Unit& u, int wr, int wc, int fr, int fq) const {
;     ...
;                 const int i0 = 32 * (wc & 1) + 8 * fq;
; #pragma unroll
;                 for (int ai = 0; ai < 2; ++ai)
; #pragma unroll
;                     for (int m = 0; m < 4; ++m) { const int row = row0 + ai * HALF + m * 16; const float rsv = __builtin_amdgcn_rsqf(rs[row] * (1.0f / 1024.0f) + 1e-6f); const int pos = row & 2047;
;                         const f32x4 c0 = *(const f32x4*)(cs + pos * 64 + i0), c1 = *(const f32x4*)(cs + pos * 64 + i0 + 4);
;                         const f32x4 s0 = *(const f32x4*)(sn + pos * 64 + i0), s1 = *(const f32x4*)(sn + pos * 64 + i0 + 4);
;                         const f32x4 x1a = acc[ai][0][m][0] * rsv, x1b = acc[ai][0][m][1] * rsv, x2a = acc[ai][1][m][0] * rsv, x2b = acc[ai][1][m][1] * rsv;
;                         bf16_t* rowp = O + (size_t)row * ldc + u.pn * BM + cw;
;                         store8(rowp, x1a * c0 - x2a * s0, x1b * c1 - x2b * s1);
;                         store8(rowp + HALF, x1a * s0 + x2a * c0, x1b * s1 + x2b * c1); }
	v_fmamk_f32 v165, v165, 0x3a800000, v237
	v_rsq_f32_e32 v176, v165
	s_nop 0
	v_pk_mul_f32 v[188:189], v[44:45], v[176:177] op_sel_hi:[1,0]
	v_pk_mul_f32 v[190:191], v[46:47], v[176:177] op_sel_hi:[1,0]
	v_pk_mul_f32 v[192:193], v[40:41], v[176:177] op_sel_hi:[1,0]
	v_pk_mul_f32 v[194:195], v[42:43], v[176:177] op_sel_hi:[1,0]
	v_pk_mul_f32 v[178:179], v[60:61], v[176:177] op_sel_hi:[1,0]
	v_pk_mul_f32 v[182:183], v[62:63], v[176:177] op_sel_hi:[1,0]
	v_pk_mul_f32 v[184:185], v[56:57], v[176:177] op_sel_hi:[1,0]
	v_pk_mul_f32 v[186:187], v[58:59], v[176:177] op_sel_hi:[1,0]
	v_pk_mul_f32 v[196:197], v[134:135], v[190:191]
	v_pk_mul_f32 v[198:199], v[132:133], v[188:189]
	v_pk_mul_f32 v[200:201], v[138:139], v[194:195]
	v_pk_mul_f32 v[202:203], v[136:137], v[192:193]
	v_pk_mul_f32 v[190:191], v[168:169], v[190:191]
	v_pk_mul_f32 v[188:189], v[166:167], v[188:189]
	v_pk_mul_f32 v[194:195], v[172:173], v[194:195]
	v_pk_mul_f32 v[192:193], v[170:171], v[192:193]
	v_pk_fma_f32 v[168:169], v[168:169], v[182:183], v[196:197] neg_lo:[0,0,1] neg_hi:[0,0,1]
	v_pk_fma_f32 v[166:167], v[166:167], v[178:179], v[198:199] neg_lo:[0,0,1] neg_hi:[0,0,1]
	v_pk_fma_f32 v[172:173], v[172:173], v[186:187], v[200:201] neg_lo:[0,0,1] neg_hi:[0,0,1]
	v_pk_fma_f32 v[170:171], v[170:171], v[184:185], v[202:203] neg_lo:[0,0,1] neg_hi:[0,0,1]
	v_pk_fma_f32 v[182:183], v[134:135], v[182:183], v[190:191]
	v_pk_fma_f32 v[178:179], v[132:133], v[178:179], v[188:189]
	v_pk_fma_f32 v[186:187], v[138:139], v[186:187], v[194:195]
	v_pk_fma_f32 v[138:139], v[136:137], v[184:185], v[192:193]
	v_cvt_pk_bf16_f32 v132, v166, v167
	v_cvt_pk_bf16_f32 v133, v168, v169
	v_cvt_pk_bf16_f32 v134, v170, v171
	v_cvt_pk_bf16_f32 v135, v172, v173
	v_cvt_pk_bf16_f32 v136, v178, v179
	v_cvt_pk_bf16_f32 v137, v182, v183
	v_cvt_pk_bf16_f32 v138, v138, v139
	v_cvt_pk_bf16_f32 v139, v186, v187
	flat_store_dwordx4 v[174:175], v[132:135]
	flat_store_dwordx4 v[174:175], v[136:139] offset:256
	flat_load_dword v165, v[128:129] offset:576
	v_add_u32_e32 v174, 0x90, v164
	v_lshlrev_b32_e32 v132, 8, v174
	v_and_b32_e32 v176, 0x7df00, v132
	v_lshl_add_u64 v[136:137], v[158:159], 0, v[176:177]
	flat_load_dwordx4 v[132:135], v[136:137]
	s_nop 0
	flat_load_dwordx4 v[136:139], v[136:137] offset:16
	v_lshl_add_u64 v[170:171], v[156:157], 0, v[176:177]
	flat_load_dwordx4 v[166:169], v[170:171]
	s_nop 0
	flat_load_dwordx4 v[170:173], v[170:171] offset:16
	v_mad_i64_i32 v[174:175], s[38:39], s82, v174, 0
	v_lshl_add_u64 v[174:175], v[174:175], 1, s[84:85]
	v_lshl_add_u64 v[174:175], v[174:175], 0, s[6:7]
	v_lshl_add_u64 v[174:175], v[174:175], 0, v[130:131]
	s_waitcnt vmcnt(0) lgkmcnt(0)
	v_fmamk_f32 v165, v165, 0x3a800000, v237
	v_rsq_f32_e32 v176, v165
	s_nop 0
	v_pk_mul_f32 v[188:189], v[28:29], v[176:177] op_sel_hi:[1,0]
	v_pk_mul_f32 v[190:191], v[30:31], v[176:177] op_sel_hi:[1,0]
	v_pk_mul_f32 v[192:193], v[24:25], v[176:177] op_sel_hi:[1,0]
	v_pk_mul_f32 v[194:195], v[26:27], v[176:177] op_sel_hi:[1,0]
	v_pk_mul_f32 v[178:179], v[52:53], v[176:177] op_sel_hi:[1,0]
	v_pk_mul_f32 v[182:183], v[54:55], v[176:177] op_sel_hi:[1,0]
	v_pk_mul_f32 v[184:185], v[48:49], v[176:177] op_sel_hi:[1,0]
	v_pk_mul_f32 v[186:187], v[50:51], v[176:177] op_sel_hi:[1,0]
	v_pk_mul_f32 v[196:197], v[134:135], v[190:191]
	v_pk_mul_f32 v[198:199], v[132:133], v[188:189]
	v_pk_mul_f32 v[200:201], v[138:139], v[194:195]
	v_pk_mul_f32 v[202:203], v[136:137], v[192:193]
	v_pk_mul_f32 v[190:191], v[168:169], v[190:191]
	v_pk_mul_f32 v[188:189], v[166:167], v[188:189]
	v_pk_mul_f32 v[194:195], v[172:173], v[194:195]
	v_pk_mul_f32 v[192:193], v[170:171], v[192:193]
	v_pk_fma_f32 v[168:169], v[168:169], v[182:183], v[196:197] neg_lo:[0,0,1] neg_hi:[0,0,1]
	v_pk_fma_f32 v[166:167], v[166:167], v[178:179], v[198:199] neg_lo:[0,0,1] neg_hi:[0,0,1]
	v_pk_fma_f32 v[172:173], v[172:173], v[186:187], v[200:201] neg_lo:[0,0,1] neg_hi:[0,0,1]
	v_pk_fma_f32 v[170:171], v[170:171], v[184:185], v[202:203] neg_lo:[0,0,1] neg_hi:[0,0,1]
	v_pk_fma_f32 v[182:183], v[134:135], v[182:183], v[190:191]
	v_pk_fma_f32 v[178:179], v[132:133], v[178:179], v[188:189]
	v_pk_fma_f32 v[186:187], v[138:139], v[186:187], v[194:195]
	v_pk_fma_f32 v[138:139], v[136:137], v[184:185], v[192:193]
	v_cvt_pk_bf16_f32 v132, v166, v167
	v_cvt_pk_bf16_f32 v133, v168, v169
	v_cvt_pk_bf16_f32 v134, v170, v171
	v_cvt_pk_bf16_f32 v135, v172, v173
	v_cvt_pk_bf16_f32 v136, v178, v179
	v_cvt_pk_bf16_f32 v137, v182, v183
	v_cvt_pk_bf16_f32 v138, v138, v139
	v_cvt_pk_bf16_f32 v139, v186, v187
	flat_store_dwordx4 v[174:175], v[132:135]
	flat_store_dwordx4 v[174:175], v[136:139] offset:256
	flat_load_dword v165, v[128:129] offset:640
	v_add_u32_e32 v174, 0xa0, v164
	v_lshlrev_b32_e32 v132, 8, v174
	v_and_b32_e32 v176, 0x7ef00, v132
	v_lshl_add_u64 v[136:137], v[158:159], 0, v[176:177]
	flat_load_dwordx4 v[132:135], v[136:137]
	s_nop 0
	flat_load_dwordx4 v[136:139], v[136:137] offset:16
	v_lshl_add_u64 v[170:171], v[156:157], 0, v[176:177]
	flat_load_dwordx4 v[166:169], v[170:171]
	s_nop 0
	flat_load_dwordx4 v[170:173], v[170:171] offset:16
	v_mad_i64_i32 v[174:175], s[38:39], s82, v174, 0
	v_lshl_add_u64 v[174:175], v[174:175], 1, s[84:85]
	v_lshl_add_u64 v[174:175], v[174:175], 0, s[6:7]
	v_lshl_add_u64 v[174:175], v[174:175], 0, v[130:131]
	s_waitcnt vmcnt(0) lgkmcnt(0)
;     __device__ __forceinline__ void operator()(const f32x4 (&acc)[2][2][4][2], const Unit& u, int wr, int wc, int fr, int fq) const {
;     ...
;                     for (int m = 0; m < 4; ++m) { const int row = row0 + ai * HALF + m * 16; const float rsv = __builtin_amdgcn_rsqf(rs[row] * (1.0f / 1024.0f) + 1e-6f); const int pos = row & 2047;
;                         const f32x4 c0 = *(const f32x4*)(cs + pos * 64 + i0), c1 = *(const f32x4*)(cs + pos * 64 + i0 + 4);
;                         const f32x4 s0 = *(const f32x4*)(sn + pos * 64 + i0), s1 = *(const f32x4*)(sn + pos * 64 + i0 + 4);
;                         const f32x4 x1a = acc[ai][0][m][0] * rsv, x1b = acc[ai][0][m][1] * rsv, x2a = acc[ai][1][m][0] * rsv, x2b = acc[ai][1][m][1] * rsv;
;                         bf16_t* rowp = O + (size_t)row * ldc + u.pn * BM + cw;
;                         store8(rowp, x1a * c0 - x2a * s0, x1b * c1 - x2b * s1);
;                         store8(rowp + HALF, x1a * s0 + x2a * c0, x1b * s1 + x2b * c1); }
	v_fmamk_f32 v165, v165, 0x3a800000, v237
	v_rsq_f32_e32 v176, v165
	s_nop 0
	v_pk_mul_f32 v[188:189], v[12:13], v[176:177] op_sel_hi:[1,0]
	v_pk_mul_f32 v[190:191], v[14:15], v[176:177] op_sel_hi:[1,0]
	v_pk_mul_f32 v[192:193], v[8:9], v[176:177] op_sel_hi:[1,0]
	v_pk_mul_f32 v[194:195], v[10:11], v[176:177] op_sel_hi:[1,0]
	v_pk_mul_f32 v[178:179], v[36:37], v[176:177] op_sel_hi:[1,0]
	v_pk_mul_f32 v[182:183], v[38:39], v[176:177] op_sel_hi:[1,0]
	v_pk_mul_f32 v[184:185], v[32:33], v[176:177] op_sel_hi:[1,0]
	v_pk_mul_f32 v[186:187], v[34:35], v[176:177] op_sel_hi:[1,0]
	v_pk_mul_f32 v[196:197], v[134:135], v[190:191]
	v_pk_mul_f32 v[198:199], v[132:133], v[188:189]
	v_pk_mul_f32 v[200:201], v[138:139], v[194:195]
	v_pk_mul_f32 v[202:203], v[136:137], v[192:193]
	v_pk_mul_f32 v[190:191], v[168:169], v[190:191]
	v_pk_mul_f32 v[188:189], v[166:167], v[188:189]
	v_pk_mul_f32 v[194:195], v[172:173], v[194:195]
	v_pk_mul_f32 v[192:193], v[170:171], v[192:193]
	v_pk_fma_f32 v[168:169], v[168:169], v[182:183], v[196:197] neg_lo:[0,0,1] neg_hi:[0,0,1]
	v_pk_fma_f32 v[166:167], v[166:167], v[178:179], v[198:199] neg_lo:[0,0,1] neg_hi:[0,0,1]
	v_pk_fma_f32 v[172:173], v[172:173], v[186:187], v[200:201] neg_lo:[0,0,1] neg_hi:[0,0,1]
	v_pk_fma_f32 v[170:171], v[170:171], v[184:185], v[202:203] neg_lo:[0,0,1] neg_hi:[0,0,1]
	v_pk_fma_f32 v[182:183], v[134:135], v[182:183], v[190:191]
	v_pk_fma_f32 v[178:179], v[132:133], v[178:179], v[188:189]
	v_pk_fma_f32 v[186:187], v[138:139], v[186:187], v[194:195]
	v_pk_fma_f32 v[138:139], v[136:137], v[184:185], v[192:193]
	v_cvt_pk_bf16_f32 v132, v166, v167
	v_cvt_pk_bf16_f32 v133, v168, v169
	v_cvt_pk_bf16_f32 v134, v170, v171
	v_cvt_pk_bf16_f32 v135, v172, v173
	v_cvt_pk_bf16_f32 v136, v178, v179
	v_cvt_pk_bf16_f32 v137, v182, v183
	v_cvt_pk_bf16_f32 v138, v138, v139
	v_cvt_pk_bf16_f32 v139, v186, v187
	flat_store_dwordx4 v[174:175], v[132:135]
	flat_store_dwordx4 v[174:175], v[136:139] offset:256
	flat_load_dword v165, v[128:129] offset:704
	v_add_u32_e32 v174, 0xb0, v164
	v_lshlrev_b32_e32 v128, 8, v174
	v_and_b32_e32 v176, 0x7ff00, v128
	v_lshl_add_u64 v[128:129], v[158:159], 0, v[176:177]
	flat_load_dwordx4 v[132:135], v[128:129]
	flat_load_dwordx4 v[136:139], v[128:129] offset:16
	v_lshl_add_u64 v[128:129], v[156:157], 0, v[176:177]
	flat_load_dwordx4 v[166:169], v[128:129]
	flat_load_dwordx4 v[170:173], v[128:129] offset:16
	v_mad_i64_i32 v[128:129], s[38:39], s82, v174, 0
	v_lshl_add_u64 v[128:129], v[128:129], 1, s[84:85]
	v_lshl_add_u64 v[128:129], v[128:129], 0, s[6:7]
	v_lshl_add_u64 v[178:179], v[128:129], 0, v[130:131]
	s_waitcnt vmcnt(0) lgkmcnt(0)
	v_fmamk_f32 v165, v165, 0x3a800000, v237
	v_rsq_f32_e32 v174, v165
	s_nop 0
	v_pk_mul_f32 v[128:129], v[20:21], v[174:175] op_sel_hi:[1,0]
	v_pk_mul_f32 v[130:131], v[22:23], v[174:175] op_sel_hi:[1,0]
	v_pk_mul_f32 v[182:183], v[16:17], v[174:175] op_sel_hi:[1,0]
	v_pk_mul_f32 v[184:185], v[18:19], v[174:175] op_sel_hi:[1,0]
	v_pk_mul_f32 v[186:187], v[4:5], v[174:175] op_sel_hi:[1,0]
	v_pk_mul_f32 v[188:189], v[6:7], v[174:175] op_sel_hi:[1,0]
	v_pk_mul_f32 v[190:191], v[0:1], v[174:175] op_sel_hi:[1,0]
	v_pk_mul_f32 v[174:175], v[2:3], v[174:175] op_sel_hi:[1,0]
	v_pk_mul_f32 v[192:193], v[134:135], v[188:189]
	v_pk_mul_f32 v[194:195], v[132:133], v[186:187]
	v_pk_mul_f32 v[196:197], v[138:139], v[174:175]
	v_pk_mul_f32 v[198:199], v[136:137], v[190:191]
	v_pk_mul_f32 v[188:189], v[168:169], v[188:189]
	v_pk_mul_f32 v[186:187], v[166:167], v[186:187]
	v_pk_mul_f32 v[174:175], v[172:173], v[174:175]
	v_pk_mul_f32 v[190:191], v[170:171], v[190:191]
	v_pk_fma_f32 v[168:169], v[168:169], v[130:131], v[192:193] neg_lo:[0,0,1] neg_hi:[0,0,1]
	v_pk_fma_f32 v[166:167], v[166:167], v[128:129], v[194:195] neg_lo:[0,0,1] neg_hi:[0,0,1]
	v_pk_fma_f32 v[172:173], v[172:173], v[184:185], v[196:197] neg_lo:[0,0,1] neg_hi:[0,0,1]
	v_pk_fma_f32 v[170:171], v[170:171], v[182:183], v[198:199] neg_lo:[0,0,1] neg_hi:[0,0,1]
	v_pk_fma_f32 v[134:135], v[134:135], v[130:131], v[188:189]
	v_pk_fma_f32 v[132:133], v[132:133], v[128:129], v[186:187]
	v_pk_fma_f32 v[138:139], v[138:139], v[184:185], v[174:175]
	v_pk_fma_f32 v[136:137], v[136:137], v[182:183], v[190:191]
	v_cvt_pk_bf16_f32 v128, v166, v167
	v_cvt_pk_bf16_f32 v129, v168, v169
	v_cvt_pk_bf16_f32 v130, v170, v171
	v_cvt_pk_bf16_f32 v131, v172, v173
	v_cvt_pk_bf16_f32 v132, v132, v133
	v_cvt_pk_bf16_f32 v133, v134, v135
	v_cvt_pk_bf16_f32 v134, v136, v137
	v_cvt_pk_bf16_f32 v135, v138, v139
	flat_store_dwordx4 v[178:179], v[128:131]
	flat_store_dwordx4 v[178:179], v[132:135] offset:256
